# decode: K chunks alternate between registers and a per-wave LDS slot (LDS-DMA), all K loads issued two steps ahead
# baseline (speedup 1.0000x reference)
.LBB0_415:
	v_mbcnt_lo_u32_b32 v0, -1, 0
	v_mbcnt_hi_u32_b32 v0, -1, v0
	v_mov_b32_e32 v182, 0x3eb8aa3b
	v_add_u32_e32 v188, s73, v0
	s_lshl_b32 s88, s93, 13
	s_add_u32 s88, s88, 0x13000
	s_add_u32 s89, s88, 0x1000
	s_cmp_eq_u32 s93, 6
	s_cselect_b32 s89, 0x20200, s89
	s_cmp_eq_u32 s93, 7
	s_cselect_b32 s88, 0x21200, s88
	s_cselect_b32 s89, 0x22200, s89
	v_lshlrev_b32_e32 v249, 4, v0
	v_add_u32_e32 v250, s89, v249
	v_add_u32_e32 v249, s88, v249
	s_nop 0
	v_readfirstlane_b32 s4, v188
	s_ashr_i32 s31, s4, 6
	s_and_b32 s24, s31, 3
	s_cmp_lt_i32 s24, 1
	s_cbranch_scc1 .LBB0_420
	s_cmp_eq_u32 s24, 1
	s_cbranch_scc1 .LBB0_418
	s_cmp_eq_u32 s24, 2
	s_cselect_b64 vcc, -1, 0
	v_cndmask_b32_e32 v182, v186, v187, vcc
	s_cbranch_execz .LBB0_419
	s_branch .LBB0_420

.LBB0_428:
	s_or_b64 exec, exec, s[40:41]
	s_and_b32 s24, s30, 7
	s_lshl_b32 s4, s24, 3
	s_and_b32 s45, s31, -4
	s_add_i32 s45, s45, s4
	s_lshl_b32 s4, s35, 6
	s_add_i32 s4, s45, s4
	s_ashr_i32 s5, s4, 31
	s_lshl_b32 s25, s31, 10
	s_lshl_b64 s[4:5], s[4:5], 2
	s_add_u32 s4, s6, s4
	s_addc_u32 s5, s7, s5
	s_waitcnt vmcnt(1)
	v_cvt_pk_bf16_f32 v60, v0, v1
	v_cvt_pk_bf16_f32 v61, v2, v3
	s_waitcnt vmcnt(0)
	v_cvt_pk_bf16_f32 v62, v4, v5
	v_cvt_pk_bf16_f32 v63, v6, v7
	global_load_dwordx4 v[0:3], v169, s[4:5]
	v_and_b32_e32 v9, 63, v188
	v_and_b32_e32 v13, 31, v188
	v_lshrrev_b32_e32 v16, 5, v9
	v_lshlrev_b32_e32 v171, 2, v13
	v_lshlrev_b32_e32 v4, 9, v16
	v_or3_b32 v8, s16, v4, v171
	s_add_i32 s16, s25, 0
	v_lshlrev_b32_e32 v168, 2, v8
	v_mov_b32_e32 v174, 0
	s_mov_b32 s51, 0
	v_or_b32_e32 v179, 0xffffe000, v12
	v_mov_b32_e32 v184, v182
	v_mov_b32_e32 v185, v182
	v_mov_b32_e32 v172, 0xf149f2ca
	s_mov_b32 s53, 0
	v_mov_b32_e32 v175, v174
	v_mov_b32_e32 v176, v174
	v_mov_b32_e32 v177, v174
	v_mov_b32_e32 v178, 0xf149f2ca
	v_mov_b32_e32 v180, 0xf149f2ca
	v_mov_b32_e32 v170, 0xf149f2ca
	s_waitcnt vmcnt(0)
	v_readfirstlane_b32 s40, v0
	s_ashr_i32 s41, s40, 31
	s_lshl_b64 s[4:5], s[40:41], 18
	s_add_u32 s42, s8, s4
	s_addc_u32 s43, s9, s5
	v_lshl_add_u64 v[4:5], s[42:43], 0, v[168:169]
	v_add_co_u32_e32 v6, vcc, s13, v4
	s_add_u32 s4, s10, s4
	s_nop 0
	v_addc_co_u32_e32 v7, vcc, 0, v5, vcc
	v_add_co_u32_e32 v10, vcc, s14, v4
	s_addc_u32 s5, s11, s5
	s_nop 0
	v_addc_co_u32_e32 v11, vcc, 0, v5, vcc
	v_add_co_u32_e32 v14, vcc, s15, v4
	v_readfirstlane_b32 s41, v1
	s_nop 0
	v_addc_co_u32_e32 v15, vcc, 0, v5, vcc
	v_add_co_u32_e32 v4, vcc, s26, v4
	v_readfirstlane_b32 s47, v2
	s_nop 0
	v_addc_co_u32_e32 v5, vcc, 0, v5, vcc
	global_load_dwordx4 v[140:143], v[6:7], off offset:-4096 nt
	global_load_dwordx4 v[136:139], v[6:7], off nt
	global_load_dwordx4 v[132:135], v[10:11], off offset:-4096 nt
	global_load_dwordx4 v[128:131], v[10:11], off nt
	global_load_dwordx4 v[124:127], v[14:15], off offset:-4096 nt
	global_load_dwordx4 v[120:123], v[14:15], off nt
	global_load_dwordx4 v[116:119], v[4:5], off nt
	v_lshl_add_u64 v[4:5], s[4:5], 0, v[168:169]
	v_add_co_u32_e32 v6, vcc, s13, v4
	global_load_dwordx4 v[144:147], v168, s[42:43] nt
	s_add_u32 s80, s42, 0x8000
	s_addc_u32 s81, s43, 0
	s_mov_b32 m0, s88
	s_nop 0
	global_load_lds_dwordx4 v168, s[80:81] nt
	s_add_u32 s80, s80, 0x1000
	s_addc_u32 s81, s81, 0
	s_add_u32 m0, m0, 0x400
	s_nop 0
	global_load_lds_dwordx4 v168, s[80:81] nt
	s_add_u32 s80, s80, 0x1000
	s_addc_u32 s81, s81, 0
	s_add_u32 m0, m0, 0x400
	s_nop 0
	global_load_lds_dwordx4 v168, s[80:81] nt
	s_add_u32 s80, s80, 0x1000
	s_addc_u32 s81, s81, 0
	s_add_u32 m0, m0, 0x400
	s_nop 0
	global_load_lds_dwordx4 v168, s[80:81] nt
	s_add_u32 s80, s80, 0x1000
	s_addc_u32 s81, s81, 0
	s_mov_b32 m0, s89
	s_nop 0
	global_load_lds_dwordx4 v168, s[80:81] nt
	s_add_u32 s80, s80, 0x1000
	s_addc_u32 s81, s81, 0
	s_add_u32 m0, m0, 0x400
	s_nop 0
	global_load_lds_dwordx4 v168, s[80:81] nt
	s_add_u32 s80, s80, 0x1000
	s_addc_u32 s81, s81, 0
	s_add_u32 m0, m0, 0x400
	s_nop 0
	global_load_lds_dwordx4 v168, s[80:81] nt
	s_add_u32 s80, s80, 0x1000
	s_addc_u32 s81, s81, 0
	s_add_u32 m0, m0, 0x400
	s_nop 0
	global_load_lds_dwordx4 v168, s[80:81] nt
	global_load_dwordx4 v[72:75], v168, s[4:5] nt
	v_addc_co_u32_e32 v7, vcc, 0, v5, vcc
	v_add_co_u32_e32 v10, vcc, s14, v4
	s_mul_i32 s4, s31, 0x1100
	s_nop 0
	v_addc_co_u32_e32 v11, vcc, 0, v5, vcc
	v_add_co_u32_e32 v14, vcc, s15, v4
	s_add_i32 s25, s4, 0
	s_nop 0
	v_addc_co_u32_e32 v15, vcc, 0, v5, vcc
	v_add_co_u32_e32 v4, vcc, s26, v4
	v_mov_b32_e32 v0, s25
	s_nop 0
	v_addc_co_u32_e32 v5, vcc, 0, v5, vcc
	global_load_dwordx4 v[80:83], v[6:7], off offset:-4096 nt
	global_load_dwordx4 v[76:79], v[6:7], off nt
	global_load_dwordx4 v[88:91], v[10:11], off offset:-4096 nt
	global_load_dwordx4 v[84:87], v[10:11], off nt
	global_load_dwordx4 v[96:99], v[14:15], off offset:-4096 nt
	global_load_dwordx4 v[92:95], v[14:15], off nt
	global_load_dwordx4 v[104:107], v[4:5], off nt
	v_lshl_add_u32 v1, v13, 3, s25
	v_cmp_gt_u32_e32 vcc, 32, v9
	v_and_b32_e32 v9, 32, v188
	v_mul_u32_u24_e32 v10, 0x110, v16
	v_mov_b32_e32 v6, v169
	v_mov_b32_e32 v7, v169
	v_readfirstlane_b32 s49, v3
	v_mad_u32_u24 v0, v12, s27, v0
	v_and_b32_e32 v2, 48, v188
	v_lshl_add_u32 v3, v12, 5, s16
	v_mov_b32_e32 v4, v169
	v_mov_b32_e32 v5, v169
	v_lshlrev_b32_e32 v168, 2, v8
	v_add_u32_e32 v181, v1, v10
	v_add_u32_e32 v173, s16, v9
	v_mov_b64_e32 v[18:19], v[6:7]
	v_mov_b64_e32 v[30:31], v[6:7]
	v_mov_b64_e32 v[38:39], v[6:7]
	v_mov_b64_e32 v[10:11], v[6:7]
	v_mov_b64_e32 v[22:23], v[6:7]
	v_mov_b64_e32 v[34:35], v[6:7]
	v_mov_b64_e32 v[46:47], v[6:7]
	v_add_u32_e32 v190, v0, v2
	v_add_u32_e32 v191, v3, v2
	v_mov_b64_e32 v[16:17], v[4:5]
	v_mov_b64_e32 v[28:29], v[4:5]
	v_mov_b64_e32 v[36:37], v[4:5]
	v_mov_b64_e32 v[8:9], v[4:5]
	v_mov_b64_e32 v[20:21], v[4:5]
	v_mov_b64_e32 v[32:33], v[4:5]
	v_mov_b64_e32 v[44:45], v[4:5]
	s_waitcnt vmcnt(16)
.LBB0_429:
	s_lshr_b32 s44, s53, 3
	s_cmp_eq_u32 s44, 2
	s_cselect_b32 s4, s47, s49
	s_cmp_eq_u32 s44, 1
	s_waitcnt vmcnt(24)
	v_cvt_pk_bf16_f32 v112, v144, v145
	v_cvt_pk_bf16_f32 v113, v146, v147
	s_cselect_b32 s4, s41, s4
	s_cmp_lt_u32 s53, 8
	ds_write_b64 v181, v[112:113] offset:43008
	v_cvt_pk_bf16_f32 v112, v140, v141
	v_cvt_pk_bf16_f32 v113, v142, v143
	s_cselect_b32 s4, s40, s4
	ds_write_b64 v181, v[112:113] offset:43552
	v_cvt_pk_bf16_f32 v112, v136, v137
	v_cvt_pk_bf16_f32 v113, v138, v139
	s_ashr_i32 s5, s4, 31
	s_and_b32 s48, s51, 0x60
	ds_write_b64 v181, v[112:113] offset:44096
	v_cvt_pk_bf16_f32 v112, v132, v133
	v_cvt_pk_bf16_f32 v113, v134, v135
	s_or_b32 s16, s48, 16
	s_lshl_b64 s[42:43], s[4:5], 18
	ds_write_b64 v181, v[112:113] offset:44640
	v_cvt_pk_bf16_f32 v112, v128, v129
	v_cvt_pk_bf16_f32 v113, v130, v131
	s_add_u32 s4, s8, s42
	ds_write_b64 v181, v[112:113] offset:45184
	v_cvt_pk_bf16_f32 v112, v124, v125
	v_cvt_pk_bf16_f32 v113, v126, v127
	s_addc_u32 s5, s9, s43
	s_lshl_b32 s46, s16, 11
	ds_write_b64 v181, v[112:113] offset:45728
	v_cvt_pk_bf16_f32 v112, v120, v121
	v_cvt_pk_bf16_f32 v113, v122, v123
	s_add_u32 s54, s4, s46
	ds_write_b64 v181, v[112:113] offset:46272
	v_cvt_pk_bf16_f32 v112, v116, v117
	v_cvt_pk_bf16_f32 v113, v118, v119
	s_addc_u32 s55, s5, 0
	ds_write_b64 v181, v[112:113] offset:46816
	v_mov_b32_e32 v183, v182
	s_add_i32 s84, s53, 2
	s_min_u32 s84, s84, 31
	s_lshr_b32 s85, s84, 3
	s_cmp_eq_u32 s85, 2
	s_cselect_b32 s86, s47, s49
	s_cmp_eq_u32 s85, 1
	s_cselect_b32 s86, s41, s86
	s_cmp_eq_u32 s85, 0
	s_cselect_b32 s86, s40, s86
	s_ashr_i32 s87, s86, 31
	s_lshl_b64 s[86:87], s[86:87], 18
	s_and_b32 s85, s84, 7
	s_lshl_b32 s85, s85, 15
	s_add_u32 s86, s86, s85
	s_addc_u32 s87, s87, 0
	s_add_u32 s86, s86, 0x1000
	s_addc_u32 s87, s87, 0
	s_add_u32 s80, s8, s86
	s_addc_u32 s81, s9, s87
	global_load_dwordx4 v[144:147], v168, s[80:81] offset:-4096 nt
	global_load_dwordx4 v[140:143], v168, s[80:81] nt
	s_add_u32 s80, s80, 0x2000
	s_addc_u32 s81, s81, 0
	global_load_dwordx4 v[136:139], v168, s[80:81] offset:-4096 nt
	global_load_dwordx4 v[132:135], v168, s[80:81] nt
	s_add_u32 s80, s80, 0x2000
	s_addc_u32 s81, s81, 0
	global_load_dwordx4 v[128:131], v168, s[80:81] offset:-4096 nt
	global_load_dwordx4 v[124:127], v168, s[80:81] nt
	s_add_u32 s80, s80, 0x2000
	s_addc_u32 s81, s81, 0
	global_load_dwordx4 v[120:123], v168, s[80:81] offset:-4096 nt
	global_load_dwordx4 v[116:119], v168, s[80:81] nt
	s_or_b32 s4, s44, s45
	s_lshl_b32 s44, s4, 7
	s_or_b32 s4, s44, s48
	v_add_u32_e32 v112, s4, v179
	v_add_u32_e32 v113, -1, v112
	v_add_u32_e32 v114, -2, v112
	v_add_u32_e32 v115, -3, v112
	s_waitcnt lgkmcnt(0)
	v_cvt_f32_i32_e32 v152, v112
	v_cvt_f32_i32_e32 v153, v113
	v_cvt_f32_i32_e32 v155, v115
	v_cvt_f32_i32_e32 v154, v114
	ds_read_b128 v[112:115], v190 offset:43008
	ds_read_b128 v[148:151], v190 offset:43072
	v_pk_mul_f32 v[152:153], v[184:185], v[152:153]
	v_pk_mul_f32 v[154:155], v[182:183], v[154:155]
	s_waitcnt lgkmcnt(1)
	s_nop 0
	v_mfma_f32_16x16x32_bf16 v[112:115], v[24:27], v[112:115], v[152:155]
	s_waitcnt lgkmcnt(0)
	v_mfma_f32_16x16x32_bf16 v[112:115], v[48:51], v[148:151], v[112:115]
	ds_read_b128 v[148:151], v190 offset:43136
	ds_read_b128 v[152:155], v190 offset:43200
	s_waitcnt lgkmcnt(1)
	v_mfma_f32_16x16x32_bf16 v[112:115], v[52:55], v[148:151], v[112:115]
	s_waitcnt lgkmcnt(0)
	v_mfma_f32_16x16x32_bf16 v[112:115], v[60:63], v[152:155], v[112:115]
	s_nop 7
	v_mov_b32_dpp v148, v112 quad_perm:[1,0,3,2] row_mask:0xf bank_mask:0xf bound_ctrl:1
	v_max_f32_e32 v149, v112, v112
	v_max_f32_e32 v148, v148, v148
	v_max_f32_e32 v148, v149, v148
	s_nop 1
	v_mov_b32_dpp v149, v148 quad_perm:[2,3,0,1] row_mask:0xf bank_mask:0xf bound_ctrl:1
	v_max_f32_e32 v149, v149, v149
	v_max_f32_e32 v148, v148, v149
	s_nop 1
	v_mov_b32_dpp v149, v148 row_half_mirror row_mask:0xf bank_mask:0xf bound_ctrl:1
	v_max_f32_e32 v149, v149, v149
	v_max_f32_e32 v148, v148, v149
	s_nop 1
	v_mov_b32_dpp v149, v148 row_ror:8 row_mask:0xf bank_mask:0xf bound_ctrl:1
	v_max3_f32 v192, v172, v148, v149
	v_mov_b32_dpp v148, v113 quad_perm:[1,0,3,2] row_mask:0xf bank_mask:0xf bound_ctrl:1
	v_max_f32_e32 v149, v113, v113
	v_max_f32_e32 v148, v148, v148
	v_max_f32_e32 v148, v149, v148
	v_sub_f32_e32 v112, v112, v192
	v_exp_f32_e32 v112, v112
	v_mov_b32_dpp v149, v148 quad_perm:[2,3,0,1] row_mask:0xf bank_mask:0xf bound_ctrl:1
	v_max_f32_e32 v149, v149, v149
	v_max_f32_e32 v148, v148, v149
	s_nop 1
	v_mov_b32_dpp v149, v148 row_half_mirror row_mask:0xf bank_mask:0xf bound_ctrl:1
	v_max_f32_e32 v149, v149, v149
	v_max_f32_e32 v148, v148, v149
	s_nop 1
	v_mov_b32_dpp v149, v148 row_ror:8 row_mask:0xf bank_mask:0xf bound_ctrl:1
	v_max3_f32 v193, v178, v148, v149
	v_mov_b32_dpp v148, v114 quad_perm:[1,0,3,2] row_mask:0xf bank_mask:0xf bound_ctrl:1
	v_max_f32_e32 v149, v114, v114
	v_max_f32_e32 v148, v148, v148
	v_max_f32_e32 v148, v149, v148
	v_sub_f32_e32 v113, v113, v193
	v_exp_f32_e32 v113, v113
	v_mov_b32_dpp v149, v148 quad_perm:[2,3,0,1] row_mask:0xf bank_mask:0xf bound_ctrl:1
	v_max_f32_e32 v149, v149, v149
	v_max_f32_e32 v148, v148, v149
	s_nop 1
	v_mov_b32_dpp v149, v148 row_half_mirror row_mask:0xf bank_mask:0xf bound_ctrl:1
	v_max_f32_e32 v149, v149, v149
	v_max_f32_e32 v148, v148, v149
	s_nop 1
	v_mov_b32_dpp v149, v148 row_ror:8 row_mask:0xf bank_mask:0xf bound_ctrl:1
	v_max3_f32 v194, v180, v148, v149
	v_mov_b32_dpp v148, v115 quad_perm:[1,0,3,2] row_mask:0xf bank_mask:0xf bound_ctrl:1
	v_max_f32_e32 v149, v115, v115
	v_max_f32_e32 v148, v148, v148
	v_max_f32_e32 v148, v149, v148
	v_sub_f32_e32 v114, v114, v194
	v_exp_f32_e32 v114, v114
	v_mov_b32_dpp v149, v148 quad_perm:[2,3,0,1] row_mask:0xf bank_mask:0xf bound_ctrl:1
	v_max_f32_e32 v149, v149, v149
	v_max_f32_e32 v148, v148, v149
	s_nop 1
	v_mov_b32_dpp v149, v148 row_half_mirror row_mask:0xf bank_mask:0xf bound_ctrl:1
	v_max_f32_e32 v149, v149, v149
	v_max_f32_e32 v148, v148, v149
	s_nop 1
	v_mov_b32_dpp v149, v148 row_ror:8 row_mask:0xf bank_mask:0xf bound_ctrl:1
	v_max3_f32 v195, v170, v148, v149
	v_sub_f32_e32 v115, v115, v195
	v_exp_f32_e32 v115, v115
	s_and_saveexec_b64 s[4:5], vcc
	ds_write_b128 v191, v[112:115] offset:34816
	s_or_b64 exec, exec, s[4:5]
	s_cmp_eq_u32 s53, 0
	s_cbranch_scc1 .LBB0_433
	s_waitcnt vmcnt(24)
	ds_read_b128 v[196:199], v173 offset:35328
	ds_read_b128 v[200:203], v173 offset:35344
	ds_read_b128 v[204:207], v173 offset:35392
	ds_read_b128 v[208:211], v173 offset:35408
	ds_read_b128 v[212:215], v173 offset:35456
	ds_read_b128 v[216:219], v173 offset:35472
	ds_read_b128 v[220:223], v173 offset:35520
	ds_read_b128 v[164:167], v173 offset:35536
	ds_read_b128 v[224:227], v173 offset:35584
	ds_read_b128 v[160:163], v173 offset:35600
	ds_read_b128 v[228:231], v173 offset:35648
	ds_read_b128 v[156:159], v173 offset:35664
	ds_read_b128 v[232:235], v173 offset:35712
	ds_read_b128 v[152:155], v173 offset:35728
	ds_read_b128 v[236:239], v173 offset:35776
	ds_read_b128 v[148:151], v173 offset:35792
	s_waitcnt lgkmcnt(14)
	v_pk_fma_f32 v[10:11], v[200:201], v[110:111], v[10:11] op_sel_hi:[0,1,1]
	v_pk_fma_f32 v[8:9], v[200:201], v[108:109], v[8:9] op_sel_hi:[0,1,1]
	v_pk_fma_f32 v[22:23], v[200:201], v[110:111], v[22:23] op_sel:[1,0,0]
	v_pk_fma_f32 v[20:21], v[200:201], v[108:109], v[20:21] op_sel:[1,0,0]
	s_waitcnt lgkmcnt(12)
	v_pk_fma_f32 v[10:11], v[208:209], v[102:103], v[10:11] op_sel_hi:[0,1,1]
	v_pk_fma_f32 v[8:9], v[208:209], v[100:101], v[8:9] op_sel_hi:[0,1,1]
	v_pk_fma_f32 v[22:23], v[208:209], v[102:103], v[22:23] op_sel:[1,0,0]
	v_pk_fma_f32 v[20:21], v[208:209], v[100:101], v[20:21] op_sel:[1,0,0]
	s_waitcnt lgkmcnt(10)
	v_pk_fma_f32 v[10:11], v[216:217], v[70:71], v[10:11] op_sel_hi:[0,1,1]
	v_pk_fma_f32 v[8:9], v[216:217], v[68:69], v[8:9] op_sel_hi:[0,1,1]
	v_pk_fma_f32 v[22:23], v[216:217], v[70:71], v[22:23] op_sel:[1,0,0]
	v_pk_fma_f32 v[20:21], v[216:217], v[68:69], v[20:21] op_sel:[1,0,0]
	s_waitcnt lgkmcnt(8)
	v_pk_fma_f32 v[10:11], v[164:165], v[66:67], v[10:11] op_sel_hi:[0,1,1]
	v_pk_fma_f32 v[8:9], v[164:165], v[64:65], v[8:9] op_sel_hi:[0,1,1]
	v_pk_fma_f32 v[22:23], v[164:165], v[66:67], v[22:23] op_sel:[1,0,0]
	v_pk_fma_f32 v[20:21], v[164:165], v[64:65], v[20:21] op_sel:[1,0,0]
	s_waitcnt lgkmcnt(6)
	v_pk_fma_f32 v[10:11], v[160:161], v[58:59], v[10:11] op_sel_hi:[0,1,1]
	v_pk_fma_f32 v[8:9], v[160:161], v[56:57], v[8:9] op_sel_hi:[0,1,1]
	v_pk_fma_f32 v[22:23], v[160:161], v[58:59], v[22:23] op_sel:[1,0,0]
	v_pk_fma_f32 v[20:21], v[160:161], v[56:57], v[20:21] op_sel:[1,0,0]
	s_waitcnt lgkmcnt(4)
	v_pk_fma_f32 v[10:11], v[156:157], v[42:43], v[10:11] op_sel_hi:[0,1,1]
	v_pk_fma_f32 v[8:9], v[156:157], v[40:41], v[8:9] op_sel_hi:[0,1,1]
	v_pk_fma_f32 v[22:23], v[156:157], v[42:43], v[22:23] op_sel:[1,0,0]
	v_pk_fma_f32 v[20:21], v[156:157], v[40:41], v[20:21] op_sel:[1,0,0]
	s_waitcnt lgkmcnt(2)
	v_pk_fma_f32 v[10:11], v[152:153], v[14:15], v[10:11] op_sel_hi:[0,1,1]
	v_pk_fma_f32 v[8:9], v[152:153], v[12:13], v[8:9] op_sel_hi:[0,1,1]
	v_pk_fma_f32 v[22:23], v[152:153], v[14:15], v[22:23] op_sel:[1,0,0]
	v_pk_fma_f32 v[20:21], v[152:153], v[12:13], v[20:21] op_sel:[1,0,0]
	s_waitcnt lgkmcnt(0)
	v_pk_fma_f32 v[10:11], v[148:149], v[2:3], v[10:11] op_sel_hi:[0,1,1]
	v_pk_fma_f32 v[8:9], v[148:149], v[0:1], v[8:9] op_sel_hi:[0,1,1]
	v_pk_fma_f32 v[22:23], v[148:149], v[2:3], v[22:23] op_sel:[1,0,0]
	v_pk_fma_f32 v[20:21], v[148:149], v[0:1], v[20:21] op_sel:[1,0,0]
	v_mov_b32_e32 v148, v199
	v_pk_fma_f32 v[38:39], v[148:149], v[110:111], v[38:39] op_sel_hi:[0,1,1]
	v_pk_fma_f32 v[36:37], v[148:149], v[108:109], v[36:37] op_sel_hi:[0,1,1]
	v_mov_b32_e32 v148, v207
	v_pk_fma_f32 v[38:39], v[148:149], v[102:103], v[38:39] op_sel_hi:[0,1,1]
	v_pk_fma_f32 v[36:37], v[148:149], v[100:101], v[36:37] op_sel_hi:[0,1,1]
	v_mov_b32_e32 v148, v215
	v_pk_fma_f32 v[38:39], v[148:149], v[70:71], v[38:39] op_sel_hi:[0,1,1]
	v_pk_fma_f32 v[36:37], v[148:149], v[68:69], v[36:37] op_sel_hi:[0,1,1]
	v_mov_b32_e32 v148, v223
	v_pk_fma_f32 v[38:39], v[148:149], v[66:67], v[38:39] op_sel_hi:[0,1,1]
	v_pk_fma_f32 v[36:37], v[148:149], v[64:65], v[36:37] op_sel_hi:[0,1,1]
	v_mov_b32_e32 v148, v227
	v_pk_fma_f32 v[38:39], v[148:149], v[58:59], v[38:39] op_sel_hi:[0,1,1]
	v_pk_fma_f32 v[36:37], v[148:149], v[56:57], v[36:37] op_sel_hi:[0,1,1]
	v_mov_b32_e32 v148, v231
	v_pk_fma_f32 v[38:39], v[148:149], v[42:43], v[38:39] op_sel_hi:[0,1,1]
	v_pk_fma_f32 v[36:37], v[148:149], v[40:41], v[36:37] op_sel_hi:[0,1,1]
	v_mov_b32_e32 v148, v235
	v_pk_fma_f32 v[38:39], v[148:149], v[14:15], v[38:39] op_sel_hi:[0,1,1]
	v_pk_fma_f32 v[36:37], v[148:149], v[12:13], v[36:37] op_sel_hi:[0,1,1]
	v_mov_b32_e32 v148, v239
	v_pk_fma_f32 v[38:39], v[148:149], v[2:3], v[38:39] op_sel_hi:[0,1,1]
	v_pk_fma_f32 v[36:37], v[148:149], v[0:1], v[36:37] op_sel_hi:[0,1,1]
	v_mov_b32_e32 v148, v203
	v_pk_fma_f32 v[6:7], v[196:197], v[110:111], v[6:7] op_sel_hi:[0,1,1]
	v_pk_fma_f32 v[4:5], v[196:197], v[108:109], v[4:5] op_sel_hi:[0,1,1]
	v_pk_fma_f32 v[18:19], v[196:197], v[110:111], v[18:19] op_sel:[1,0,0]
	v_pk_fma_f32 v[16:17], v[196:197], v[108:109], v[16:17] op_sel:[1,0,0]
	v_pk_fma_f32 v[30:31], v[198:199], v[110:111], v[30:31] op_sel_hi:[0,1,1]
	v_pk_fma_f32 v[28:29], v[198:199], v[108:109], v[28:29] op_sel_hi:[0,1,1]
	v_pk_fma_f32 v[34:35], v[202:203], v[110:111], v[34:35] op_sel_hi:[0,1,1]
	v_pk_fma_f32 v[32:33], v[202:203], v[108:109], v[32:33] op_sel_hi:[0,1,1]
	v_pk_fma_f32 v[46:47], v[148:149], v[110:111], v[46:47] op_sel_hi:[0,1,1]
	v_pk_fma_f32 v[44:45], v[148:149], v[108:109], v[44:45] op_sel_hi:[0,1,1]
	v_mov_b32_e32 v108, v211
	v_pk_fma_f32 v[6:7], v[204:205], v[102:103], v[6:7] op_sel_hi:[0,1,1]
	v_pk_fma_f32 v[4:5], v[204:205], v[100:101], v[4:5] op_sel_hi:[0,1,1]
	v_pk_fma_f32 v[18:19], v[204:205], v[102:103], v[18:19] op_sel:[1,0,0]
	v_pk_fma_f32 v[16:17], v[204:205], v[100:101], v[16:17] op_sel:[1,0,0]
	v_pk_fma_f32 v[30:31], v[206:207], v[102:103], v[30:31] op_sel_hi:[0,1,1]
	v_pk_fma_f32 v[28:29], v[206:207], v[100:101], v[28:29] op_sel_hi:[0,1,1]
	v_pk_fma_f32 v[34:35], v[210:211], v[102:103], v[34:35] op_sel_hi:[0,1,1]
	v_pk_fma_f32 v[32:33], v[210:211], v[100:101], v[32:33] op_sel_hi:[0,1,1]
	v_pk_fma_f32 v[46:47], v[108:109], v[102:103], v[46:47] op_sel_hi:[0,1,1]
	v_pk_fma_f32 v[44:45], v[108:109], v[100:101], v[44:45] op_sel_hi:[0,1,1]
	v_mov_b32_e32 v100, v219
	v_pk_fma_f32 v[6:7], v[212:213], v[70:71], v[6:7] op_sel_hi:[0,1,1]
	v_pk_fma_f32 v[4:5], v[212:213], v[68:69], v[4:5] op_sel_hi:[0,1,1]
	v_pk_fma_f32 v[18:19], v[212:213], v[70:71], v[18:19] op_sel:[1,0,0]
	v_pk_fma_f32 v[16:17], v[212:213], v[68:69], v[16:17] op_sel:[1,0,0]
	v_pk_fma_f32 v[30:31], v[214:215], v[70:71], v[30:31] op_sel_hi:[0,1,1]
	v_pk_fma_f32 v[28:29], v[214:215], v[68:69], v[28:29] op_sel_hi:[0,1,1]
	v_pk_fma_f32 v[34:35], v[218:219], v[70:71], v[34:35] op_sel_hi:[0,1,1]
	v_pk_fma_f32 v[32:33], v[218:219], v[68:69], v[32:33] op_sel_hi:[0,1,1]
	v_pk_fma_f32 v[46:47], v[100:101], v[70:71], v[46:47] op_sel_hi:[0,1,1]
	v_pk_fma_f32 v[44:45], v[100:101], v[68:69], v[44:45] op_sel_hi:[0,1,1]
	v_mov_b32_e32 v68, v167
	v_pk_fma_f32 v[6:7], v[220:221], v[66:67], v[6:7] op_sel_hi:[0,1,1]
	v_pk_fma_f32 v[4:5], v[220:221], v[64:65], v[4:5] op_sel_hi:[0,1,1]
	v_pk_fma_f32 v[18:19], v[220:221], v[66:67], v[18:19] op_sel:[1,0,0]
	v_pk_fma_f32 v[16:17], v[220:221], v[64:65], v[16:17] op_sel:[1,0,0]
	v_pk_fma_f32 v[30:31], v[222:223], v[66:67], v[30:31] op_sel_hi:[0,1,1]
	v_pk_fma_f32 v[28:29], v[222:223], v[64:65], v[28:29] op_sel_hi:[0,1,1]
	v_pk_fma_f32 v[34:35], v[166:167], v[66:67], v[34:35] op_sel_hi:[0,1,1]
	v_pk_fma_f32 v[32:33], v[166:167], v[64:65], v[32:33] op_sel_hi:[0,1,1]
	v_pk_fma_f32 v[46:47], v[68:69], v[66:67], v[46:47] op_sel_hi:[0,1,1]
	v_pk_fma_f32 v[44:45], v[68:69], v[64:65], v[44:45] op_sel_hi:[0,1,1]
	v_mov_b32_e32 v64, v163
	v_pk_fma_f32 v[6:7], v[224:225], v[58:59], v[6:7] op_sel_hi:[0,1,1]
	v_pk_fma_f32 v[4:5], v[224:225], v[56:57], v[4:5] op_sel_hi:[0,1,1]
	v_pk_fma_f32 v[18:19], v[224:225], v[58:59], v[18:19] op_sel:[1,0,0]
	v_pk_fma_f32 v[16:17], v[224:225], v[56:57], v[16:17] op_sel:[1,0,0]
	v_pk_fma_f32 v[30:31], v[226:227], v[58:59], v[30:31] op_sel_hi:[0,1,1]
	v_pk_fma_f32 v[28:29], v[226:227], v[56:57], v[28:29] op_sel_hi:[0,1,1]
	v_pk_fma_f32 v[34:35], v[162:163], v[58:59], v[34:35] op_sel_hi:[0,1,1]
	v_pk_fma_f32 v[32:33], v[162:163], v[56:57], v[32:33] op_sel_hi:[0,1,1]
	v_pk_fma_f32 v[46:47], v[64:65], v[58:59], v[46:47] op_sel_hi:[0,1,1]
	v_pk_fma_f32 v[44:45], v[64:65], v[56:57], v[44:45] op_sel_hi:[0,1,1]
	v_mov_b32_e32 v56, v159
	v_pk_fma_f32 v[6:7], v[228:229], v[42:43], v[6:7] op_sel_hi:[0,1,1]
	v_pk_fma_f32 v[4:5], v[228:229], v[40:41], v[4:5] op_sel_hi:[0,1,1]
	v_pk_fma_f32 v[18:19], v[228:229], v[42:43], v[18:19] op_sel:[1,0,0]
	v_pk_fma_f32 v[16:17], v[228:229], v[40:41], v[16:17] op_sel:[1,0,0]
	v_pk_fma_f32 v[30:31], v[230:231], v[42:43], v[30:31] op_sel_hi:[0,1,1]
	v_pk_fma_f32 v[28:29], v[230:231], v[40:41], v[28:29] op_sel_hi:[0,1,1]
	v_pk_fma_f32 v[34:35], v[158:159], v[42:43], v[34:35] op_sel_hi:[0,1,1]
	v_pk_fma_f32 v[32:33], v[158:159], v[40:41], v[32:33] op_sel_hi:[0,1,1]
	v_pk_fma_f32 v[42:43], v[56:57], v[42:43], v[46:47] op_sel_hi:[0,1,1]
	v_pk_fma_f32 v[40:41], v[56:57], v[40:41], v[44:45] op_sel_hi:[0,1,1]
	v_mov_b32_e32 v44, v155
	v_pk_fma_f32 v[6:7], v[232:233], v[14:15], v[6:7] op_sel_hi:[0,1,1]
	v_pk_fma_f32 v[4:5], v[232:233], v[12:13], v[4:5] op_sel_hi:[0,1,1]
	v_pk_fma_f32 v[18:19], v[232:233], v[14:15], v[18:19] op_sel:[1,0,0]
	v_pk_fma_f32 v[16:17], v[232:233], v[12:13], v[16:17] op_sel:[1,0,0]
	v_pk_fma_f32 v[30:31], v[234:235], v[14:15], v[30:31] op_sel_hi:[0,1,1]
	v_pk_fma_f32 v[28:29], v[234:235], v[12:13], v[28:29] op_sel_hi:[0,1,1]
	v_pk_fma_f32 v[34:35], v[154:155], v[14:15], v[34:35] op_sel_hi:[0,1,1]
	v_pk_fma_f32 v[32:33], v[154:155], v[12:13], v[32:33] op_sel_hi:[0,1,1]
	v_pk_fma_f32 v[14:15], v[44:45], v[14:15], v[42:43] op_sel_hi:[0,1,1]
	v_pk_fma_f32 v[12:13], v[44:45], v[12:13], v[40:41] op_sel_hi:[0,1,1]
	v_mov_b32_e32 v40, v151
	v_pk_fma_f32 v[6:7], v[236:237], v[2:3], v[6:7] op_sel_hi:[0,1,1]
	v_pk_fma_f32 v[4:5], v[236:237], v[0:1], v[4:5] op_sel_hi:[0,1,1]
	v_pk_fma_f32 v[18:19], v[236:237], v[2:3], v[18:19] op_sel:[1,0,0]
	v_pk_fma_f32 v[16:17], v[236:237], v[0:1], v[16:17] op_sel:[1,0,0]
	v_pk_fma_f32 v[30:31], v[238:239], v[2:3], v[30:31] op_sel_hi:[0,1,1]
	v_pk_fma_f32 v[28:29], v[238:239], v[0:1], v[28:29] op_sel_hi:[0,1,1]
	v_pk_fma_f32 v[34:35], v[150:151], v[2:3], v[34:35] op_sel_hi:[0,1,1]
	v_pk_fma_f32 v[32:33], v[150:151], v[0:1], v[32:33] op_sel_hi:[0,1,1]
	v_pk_fma_f32 v[46:47], v[40:41], v[2:3], v[14:15] op_sel_hi:[0,1,1]
	v_pk_fma_f32 v[44:45], v[40:41], v[0:1], v[12:13] op_sel_hi:[0,1,1]
.LBB0_433:
	s_add_u32 s4, s10, s42
	v_sub_f32_e32 v0, v172, v192
	s_addc_u32 s5, s11, s43
	v_exp_f32_e32 v152, v0
	v_sub_f32_e32 v0, v178, v193
	s_add_u32 s42, s4, s46
	v_exp_f32_e32 v153, v0
	v_sub_f32_e32 v0, v180, v194
	s_addc_u32 s43, s5, 0
	v_exp_f32_e32 v154, v0
	v_lshl_add_u64 v[0:1], s[42:43], 0, v[168:169]
	v_add_co_u32_e64 v2, s[4:5], s13, v0
	v_mov_b32_e32 v183, v182
	s_nop 0
	v_addc_co_u32_e64 v3, s[4:5], 0, v1, s[4:5]
	global_load_dwordx4 v[100:103], v[2:3], off offset:-4096 nt
	global_load_dwordx4 v[68:71], v[2:3], off nt
	v_add_co_u32_e64 v2, s[4:5], s14, v0
	v_sub_f32_e32 v155, v170, v195
	s_nop 0
	v_addc_co_u32_e64 v3, s[4:5], 0, v1, s[4:5]
	global_load_dwordx4 v[64:67], v[2:3], off offset:-4096 nt
	global_load_dwordx4 v[56:59], v[2:3], off nt
	v_add_co_u32_e64 v2, s[4:5], s15, v0
	v_exp_f32_e32 v155, v155
	s_nop 0
	v_addc_co_u32_e64 v3, s[4:5], 0, v1, s[4:5]
	v_add_co_u32_e64 v0, s[4:5], s26, v0
	global_load_dwordx4 v[40:43], v[2:3], off offset:-4096 nt
	global_load_dwordx4 v[12:15], v[2:3], off nt
	v_addc_co_u32_e64 v1, s[4:5], 0, v1, s[4:5]
	s_min_u32 s4, s53, 29
	global_load_dwordx4 v[108:111], v168, s[42:43] nt
	s_nop 0
	global_load_dwordx4 v[0:3], v[0:1], off nt
	s_add_i32 s42, s4, 2
	s_lshr_b32 s4, s42, 3
	s_cmp_eq_u32 s4, 2
	s_cselect_b32 s5, s47, s49
	s_cmp_eq_u32 s4, 1
	s_cselect_b32 s4, s41, s5
	s_cmp_lt_u32 s53, 6
	s_cselect_b32 s4, s40, s4
	s_ashr_i32 s5, s4, 31
	s_lshl_b32 s42, s42, 15
	s_and_b32 s55, s42, 0x38000
	s_lshl_b64 s[42:43], s[4:5], 18
	s_add_u32 s4, s8, s42
	s_addc_u32 s5, s9, s43
	s_add_u32 s56, s4, s55
	s_waitcnt lgkmcnt(0)
	s_waitcnt vmcnt(24)
	ds_read_b128 v[196:199], v249
	ds_read_b128 v[200:203], v249 offset:1024
	ds_read_b128 v[204:207], v249 offset:2048
	ds_read_b128 v[208:211], v249 offset:3072
	ds_read_b128 v[212:215], v250
	ds_read_b128 v[216:219], v250 offset:1024
	ds_read_b128 v[220:223], v250 offset:2048
	ds_read_b128 v[224:227], v250 offset:3072
	s_waitcnt lgkmcnt(0)
	v_cvt_pk_bf16_f32 v196, v196, v197
	v_cvt_pk_bf16_f32 v197, v198, v199
	ds_write_b64 v181, v[196:197] offset:43008
	v_cvt_pk_bf16_f32 v200, v200, v201
	v_cvt_pk_bf16_f32 v201, v202, v203
	ds_write_b64 v181, v[200:201] offset:43552
	v_cvt_pk_bf16_f32 v204, v204, v205
	v_cvt_pk_bf16_f32 v205, v206, v207
	ds_write_b64 v181, v[204:205] offset:44096
	v_cvt_pk_bf16_f32 v208, v208, v209
	v_cvt_pk_bf16_f32 v209, v210, v211
	ds_write_b64 v181, v[208:209] offset:44640
	v_cvt_pk_bf16_f32 v212, v212, v213
	v_cvt_pk_bf16_f32 v213, v214, v215
	ds_write_b64 v181, v[212:213] offset:45184
	v_cvt_pk_bf16_f32 v216, v216, v217
	v_cvt_pk_bf16_f32 v217, v218, v219
	ds_write_b64 v181, v[216:217] offset:45728
	v_cvt_pk_bf16_f32 v220, v220, v221
	v_cvt_pk_bf16_f32 v221, v222, v223
	ds_write_b64 v181, v[220:221] offset:46272
	v_cvt_pk_bf16_f32 v224, v224, v225
	v_cvt_pk_bf16_f32 v225, v226, v227
	s_addc_u32 s57, s5, 0
	ds_write_b64 v181, v[224:225] offset:46816
	v_readlane_b32 s48, v152, 0
	v_readlane_b32 s46, v152, 16
	v_readlane_b32 s54, v154, 16
	s_add_i32 s84, s53, 3
	s_min_u32 s84, s84, 31
	s_lshr_b32 s85, s84, 3
	s_cmp_eq_u32 s85, 2
	s_cselect_b32 s86, s47, s49
	s_cmp_eq_u32 s85, 1
	s_cselect_b32 s86, s41, s86
	s_cmp_eq_u32 s85, 0
	s_cselect_b32 s86, s40, s86
	s_ashr_i32 s87, s86, 31
	s_lshl_b64 s[86:87], s[86:87], 18
	s_and_b32 s85, s84, 7
	s_lshl_b32 s85, s85, 15
	s_add_u32 s86, s86, s85
	s_addc_u32 s87, s87, 0
	s_add_u32 s80, s8, s86
	s_addc_u32 s81, s9, s87
	s_mov_b32 m0, s88
	s_nop 0
	global_load_lds_dwordx4 v168, s[80:81] nt
	s_add_u32 s80, s80, 0x1000
	s_addc_u32 s81, s81, 0
	s_add_u32 m0, m0, 0x400
	s_nop 0
	global_load_lds_dwordx4 v168, s[80:81] nt
	s_add_u32 s80, s80, 0x1000
	s_addc_u32 s81, s81, 0
	s_add_u32 m0, m0, 0x400
	s_nop 0
	global_load_lds_dwordx4 v168, s[80:81] nt
	s_add_u32 s80, s80, 0x1000
	s_addc_u32 s81, s81, 0
	s_add_u32 m0, m0, 0x400
	s_nop 0
	global_load_lds_dwordx4 v168, s[80:81] nt
	s_add_u32 s80, s80, 0x1000
	s_addc_u32 s81, s81, 0
	s_mov_b32 m0, s89
	s_nop 0
	global_load_lds_dwordx4 v168, s[80:81] nt
	s_add_u32 s80, s80, 0x1000
	s_addc_u32 s81, s81, 0
	s_add_u32 m0, m0, 0x400
	s_nop 0
	global_load_lds_dwordx4 v168, s[80:81] nt
	s_add_u32 s80, s80, 0x1000
	s_addc_u32 s81, s81, 0
	s_add_u32 m0, m0, 0x400
	s_nop 0
	global_load_lds_dwordx4 v168, s[80:81] nt
	s_add_u32 s80, s80, 0x1000
	s_addc_u32 s81, s81, 0
	s_add_u32 m0, m0, 0x400
	s_nop 0
	global_load_lds_dwordx4 v168, s[80:81] nt
	s_or_b32 s4, s44, s16
	v_add_u32_e32 v148, s4, v179
	v_add_u32_e32 v149, -1, v148
	v_add_u32_e32 v150, -2, v148
	v_add_u32_e32 v151, -3, v148
	s_waitcnt lgkmcnt(0)
	v_cvt_f32_i32_e32 v160, v148
	v_cvt_f32_i32_e32 v161, v149
	v_cvt_f32_i32_e32 v163, v151
	v_cvt_f32_i32_e32 v162, v150
	ds_read_b128 v[148:151], v190 offset:43008
	ds_read_b128 v[156:159], v190 offset:43072
	v_pk_mul_f32 v[160:161], v[184:185], v[160:161]
	v_readlane_b32 s44, v153, 0
	v_pk_mul_f32 v[162:163], v[182:183], v[162:163]
	v_readlane_b32 s16, v153, 16
	v_readlane_b32 s4, v154, 0
	s_waitcnt lgkmcnt(1)
	v_mfma_f32_16x16x32_bf16 v[148:151], v[24:27], v[148:151], v[160:163]
	v_readlane_b32 s52, v155, 0
	v_readlane_b32 s50, v155, 16
	s_nop 0
	ds_read_b128 v[160:163], v190 offset:43136
	s_waitcnt lgkmcnt(1)
	v_mfma_f32_16x16x32_bf16 v[148:151], v[48:51], v[156:159], v[148:151]
	ds_read_b128 v[156:159], v190 offset:43200
	s_waitcnt lgkmcnt(1)
	v_mfma_f32_16x16x32_bf16 v[148:151], v[52:55], v[160:163], v[148:151]
	s_waitcnt lgkmcnt(0)
	v_mfma_f32_16x16x32_bf16 v[148:151], v[60:63], v[156:159], v[148:151]
	s_nop 7
	v_mov_b32_dpp v156, v148 quad_perm:[1,0,3,2] row_mask:0xf bank_mask:0xf bound_ctrl:1
	v_max_f32_e32 v157, v148, v148
	v_max_f32_e32 v156, v156, v156
	v_max_f32_e32 v156, v157, v156
	s_nop 1
	v_mov_b32_dpp v157, v156 quad_perm:[2,3,0,1] row_mask:0xf bank_mask:0xf bound_ctrl:1
	v_max_f32_e32 v157, v157, v157
	v_max_f32_e32 v156, v156, v157
	s_nop 1
	v_mov_b32_dpp v157, v156 row_half_mirror row_mask:0xf bank_mask:0xf bound_ctrl:1
	v_max_f32_e32 v157, v157, v157
	v_max_f32_e32 v156, v156, v157
	s_nop 1
	v_mov_b32_dpp v157, v156 row_ror:8 row_mask:0xf bank_mask:0xf bound_ctrl:1
	v_max3_f32 v172, v192, v156, v157
	v_mov_b32_dpp v156, v149 quad_perm:[1,0,3,2] row_mask:0xf bank_mask:0xf bound_ctrl:1
	v_max_f32_e32 v157, v149, v149
	v_max_f32_e32 v156, v156, v156
	v_max_f32_e32 v156, v157, v156
	v_sub_f32_e32 v148, v148, v172
	v_exp_f32_e32 v148, v148
	v_mov_b32_dpp v157, v156 quad_perm:[2,3,0,1] row_mask:0xf bank_mask:0xf bound_ctrl:1
	v_max_f32_e32 v157, v157, v157
	v_max_f32_e32 v156, v156, v157
	s_nop 1
	v_mov_b32_dpp v157, v156 row_half_mirror row_mask:0xf bank_mask:0xf bound_ctrl:1
	v_max_f32_e32 v157, v157, v157
	v_max_f32_e32 v156, v156, v157
	s_nop 1
	v_mov_b32_dpp v157, v156 row_ror:8 row_mask:0xf bank_mask:0xf bound_ctrl:1
	v_max3_f32 v178, v193, v156, v157
	v_mov_b32_dpp v156, v150 quad_perm:[1,0,3,2] row_mask:0xf bank_mask:0xf bound_ctrl:1
	v_max_f32_e32 v157, v150, v150
	v_max_f32_e32 v156, v156, v156
	v_max_f32_e32 v156, v157, v156
	v_sub_f32_e32 v149, v149, v178
	v_exp_f32_e32 v149, v149
	v_mov_b32_dpp v157, v156 quad_perm:[2,3,0,1] row_mask:0xf bank_mask:0xf bound_ctrl:1
	v_max_f32_e32 v157, v157, v157
	v_max_f32_e32 v156, v156, v157
	s_nop 1
	v_mov_b32_dpp v157, v156 row_half_mirror row_mask:0xf bank_mask:0xf bound_ctrl:1
	v_max_f32_e32 v157, v157, v157
	v_max_f32_e32 v156, v156, v157
	s_nop 1
	v_mov_b32_dpp v157, v156 row_ror:8 row_mask:0xf bank_mask:0xf bound_ctrl:1
	v_max3_f32 v180, v194, v156, v157
	v_mov_b32_dpp v156, v151 quad_perm:[1,0,3,2] row_mask:0xf bank_mask:0xf bound_ctrl:1
	v_max_f32_e32 v157, v151, v151
	v_max_f32_e32 v156, v156, v156
	v_max_f32_e32 v156, v157, v156
	v_sub_f32_e32 v150, v150, v180
	v_exp_f32_e32 v150, v150
	v_mov_b32_dpp v157, v156 quad_perm:[2,3,0,1] row_mask:0xf bank_mask:0xf bound_ctrl:1
	v_max_f32_e32 v157, v157, v157
	v_max_f32_e32 v156, v156, v157
	s_nop 1
	v_mov_b32_dpp v157, v156 row_half_mirror row_mask:0xf bank_mask:0xf bound_ctrl:1
	v_max_f32_e32 v157, v157, v157
	v_max_f32_e32 v156, v156, v157
	s_nop 1
	v_mov_b32_dpp v157, v156 row_ror:8 row_mask:0xf bank_mask:0xf bound_ctrl:1
	v_max3_f32 v170, v195, v156, v157
	v_sub_f32_e32 v151, v151, v170
	v_exp_f32_e32 v151, v151
	s_and_saveexec_b64 s[56:57], vcc
	ds_write_b128 v191, v[148:151] offset:35328
	s_or_b64 exec, exec, s[56:57]
	v_pk_mul_f32 v[216:217], v[6:7], s[48:49] op_sel_hi:[1,0]
	v_pk_mul_f32 v[218:219], v[4:5], s[48:49] op_sel_hi:[1,0]
	v_pk_mul_f32 v[220:221], v[10:11], s[46:47] op_sel_hi:[1,0]
	v_pk_mul_f32 v[222:223], v[8:9], s[46:47] op_sel_hi:[1,0]
	v_pk_mul_f32 v[224:225], v[18:19], s[44:45] op_sel_hi:[1,0]
	v_pk_mul_f32 v[226:227], v[16:17], s[44:45] op_sel_hi:[1,0]
	v_pk_mul_f32 v[228:229], v[22:23], s[16:17] op_sel_hi:[1,0]
	v_pk_mul_f32 v[230:231], v[20:21], s[16:17] op_sel_hi:[1,0]
	v_pk_mul_f32 v[232:233], v[30:31], s[4:5] op_sel_hi:[1,0]
	v_pk_mul_f32 v[234:235], v[28:29], s[4:5] op_sel_hi:[1,0]
	v_pk_mul_f32 v[236:237], v[34:35], s[54:55] op_sel_hi:[1,0]
	v_pk_mul_f32 v[238:239], v[32:33], s[54:55] op_sel_hi:[1,0]
	v_pk_mul_f32 v[240:241], v[38:39], s[52:53] op_sel_hi:[1,0]
	v_pk_mul_f32 v[242:243], v[36:37], s[52:53] op_sel_hi:[1,0]
	v_pk_mul_f32 v[244:245], v[46:47], s[50:51] op_sel_hi:[1,0]
	v_pk_mul_f32 v[246:247], v[44:45], s[50:51] op_sel_hi:[1,0]
	s_waitcnt vmcnt(24)
	ds_read_b128 v[4:7], v173 offset:34816
	ds_read_b128 v[8:11], v173 offset:34832
	ds_read_b128 v[16:19], v173 offset:34880
	ds_read_b128 v[20:23], v173 offset:34896
	ds_read_b128 v[28:31], v173 offset:34944
	ds_read_b128 v[32:35], v173 offset:34960
	ds_read_b128 v[36:39], v173 offset:35008
	ds_read_b128 v[44:47], v173 offset:35024
	ds_read_b128 v[156:159], v173 offset:35072
	ds_read_b128 v[160:163], v173 offset:35088
	ds_read_b128 v[164:167], v173 offset:35136
	ds_read_b128 v[196:199], v173 offset:35152
	ds_read_b128 v[200:203], v173 offset:35200
	ds_read_b128 v[204:207], v173 offset:35216
	ds_read_b128 v[208:211], v173 offset:35264
	ds_read_b128 v[212:215], v173 offset:35280
	s_waitcnt lgkmcnt(14)
	v_pk_fma_f32 v[216:217], v[4:5], v[74:75], v[216:217] op_sel_hi:[0,1,1]
	v_pk_fma_f32 v[218:219], v[4:5], v[72:73], v[218:219] op_sel_hi:[0,1,1]
	v_pk_fma_f32 v[224:225], v[4:5], v[74:75], v[224:225] op_sel:[1,0,0]
	v_pk_fma_f32 v[4:5], v[4:5], v[72:73], v[226:227] op_sel:[1,0,0]
	s_waitcnt lgkmcnt(13)
	v_pk_fma_f32 v[218:219], v[16:17], v[80:81], v[218:219] op_sel_hi:[0,1,1]
	v_pk_fma_f32 v[4:5], v[16:17], v[80:81], v[4:5] op_sel:[1,0,0]
	v_pk_fma_f32 v[216:217], v[16:17], v[82:83], v[216:217] op_sel_hi:[0,1,1]
	s_waitcnt lgkmcnt(11)
	v_pk_fma_f32 v[4:5], v[28:29], v[76:77], v[4:5] op_sel:[1,0,0]
	v_pk_fma_f32 v[16:17], v[16:17], v[82:83], v[224:225] op_sel:[1,0,0]
	s_waitcnt lgkmcnt(9)
	v_pk_fma_f32 v[4:5], v[36:37], v[88:89], v[4:5] op_sel:[1,0,0]
	v_pk_fma_f32 v[216:217], v[28:29], v[78:79], v[216:217] op_sel_hi:[0,1,1]
	s_waitcnt lgkmcnt(7)
	v_pk_fma_f32 v[4:5], v[156:157], v[84:85], v[4:5] op_sel:[1,0,0]
	v_pk_fma_f32 v[218:219], v[28:29], v[76:77], v[218:219] op_sel_hi:[0,1,1]
	s_waitcnt lgkmcnt(5)
	v_pk_fma_f32 v[4:5], v[164:165], v[96:97], v[4:5] op_sel:[1,0,0]
	v_pk_fma_f32 v[16:17], v[28:29], v[78:79], v[16:17] op_sel:[1,0,0]
	s_waitcnt lgkmcnt(3)
	v_pk_fma_f32 v[4:5], v[200:201], v[92:93], v[4:5] op_sel:[1,0,0]
	v_pk_fma_f32 v[220:221], v[8:9], v[74:75], v[220:221] op_sel_hi:[0,1,1]
	s_waitcnt lgkmcnt(1)
	v_pk_fma_f32 v[28:29], v[208:209], v[104:105], v[4:5] op_sel:[1,0,0]
	v_pk_fma_f32 v[4:5], v[8:9], v[74:75], v[228:229] op_sel:[1,0,0]
	v_pk_fma_f32 v[222:223], v[8:9], v[72:73], v[222:223] op_sel_hi:[0,1,1]
	v_pk_fma_f32 v[8:9], v[8:9], v[72:73], v[230:231] op_sel:[1,0,0]
	v_pk_fma_f32 v[4:5], v[20:21], v[82:83], v[4:5] op_sel:[1,0,0]
	v_pk_fma_f32 v[8:9], v[20:21], v[80:81], v[8:9] op_sel:[1,0,0]
	v_pk_fma_f32 v[4:5], v[32:33], v[78:79], v[4:5] op_sel:[1,0,0]
	v_pk_fma_f32 v[8:9], v[32:33], v[76:77], v[8:9] op_sel:[1,0,0]
	v_pk_fma_f32 v[4:5], v[44:45], v[90:91], v[4:5] op_sel:[1,0,0]
	v_pk_fma_f32 v[8:9], v[44:45], v[88:89], v[8:9] op_sel:[1,0,0]
	v_pk_fma_f32 v[4:5], v[160:161], v[86:87], v[4:5] op_sel:[1,0,0]
	v_pk_fma_f32 v[8:9], v[160:161], v[84:85], v[8:9] op_sel:[1,0,0]
	v_pk_fma_f32 v[4:5], v[196:197], v[98:99], v[4:5] op_sel:[1,0,0]
	v_pk_fma_f32 v[222:223], v[20:21], v[80:81], v[222:223] op_sel_hi:[0,1,1]
	v_pk_fma_f32 v[220:221], v[20:21], v[82:83], v[220:221] op_sel_hi:[0,1,1]
	v_pk_fma_f32 v[8:9], v[196:197], v[96:97], v[8:9] op_sel:[1,0,0]
	v_pk_fma_f32 v[4:5], v[204:205], v[94:95], v[4:5] op_sel:[1,0,0]
	v_pk_fma_f32 v[220:221], v[32:33], v[78:79], v[220:221] op_sel_hi:[0,1,1]
	v_pk_fma_f32 v[222:223], v[32:33], v[76:77], v[222:223] op_sel_hi:[0,1,1]
	v_pk_fma_f32 v[8:9], v[204:205], v[92:93], v[8:9] op_sel:[1,0,0]
	s_waitcnt lgkmcnt(0)
	v_pk_fma_f32 v[32:33], v[212:213], v[106:107], v[4:5] op_sel:[1,0,0]
	v_pk_fma_f32 v[4:5], v[6:7], v[74:75], v[232:233] op_sel_hi:[0,1,1]
	v_pk_fma_f32 v[20:21], v[212:213], v[104:105], v[8:9] op_sel:[1,0,0]
	v_pk_fma_f32 v[8:9], v[6:7], v[72:73], v[234:235] op_sel_hi:[0,1,1]
	v_pk_fma_f32 v[4:5], v[18:19], v[82:83], v[4:5] op_sel_hi:[0,1,1]
	v_pk_fma_f32 v[8:9], v[18:19], v[80:81], v[8:9] op_sel_hi:[0,1,1]
	v_pk_fma_f32 v[4:5], v[30:31], v[78:79], v[4:5] op_sel_hi:[0,1,1]
	v_pk_fma_f32 v[8:9], v[30:31], v[76:77], v[8:9] op_sel_hi:[0,1,1]
	v_pk_fma_f32 v[4:5], v[38:39], v[90:91], v[4:5] op_sel_hi:[0,1,1]
	v_pk_fma_f32 v[8:9], v[38:39], v[88:89], v[8:9] op_sel_hi:[0,1,1]
	v_pk_fma_f32 v[4:5], v[158:159], v[86:87], v[4:5] op_sel_hi:[0,1,1]
	v_pk_fma_f32 v[8:9], v[158:159], v[84:85], v[8:9] op_sel_hi:[0,1,1]
	v_pk_fma_f32 v[4:5], v[166:167], v[98:99], v[4:5] op_sel_hi:[0,1,1]
	v_pk_fma_f32 v[8:9], v[166:167], v[96:97], v[8:9] op_sel_hi:[0,1,1]
	v_pk_fma_f32 v[4:5], v[202:203], v[94:95], v[4:5] op_sel_hi:[0,1,1]
	v_pk_fma_f32 v[222:223], v[44:45], v[88:89], v[222:223] op_sel_hi:[0,1,1]
	v_pk_fma_f32 v[220:221], v[44:45], v[90:91], v[220:221] op_sel_hi:[0,1,1]
	v_pk_fma_f32 v[8:9], v[202:203], v[92:93], v[8:9] op_sel_hi:[0,1,1]
	v_pk_fma_f32 v[44:45], v[210:211], v[106:107], v[4:5] op_sel_hi:[0,1,1]
	v_pk_fma_f32 v[4:5], v[10:11], v[74:75], v[236:237] op_sel_hi:[0,1,1]
	v_pk_fma_f32 v[218:219], v[36:37], v[88:89], v[218:219] op_sel_hi:[0,1,1]
	v_pk_fma_f32 v[216:217], v[36:37], v[90:91], v[216:217] op_sel_hi:[0,1,1]
	v_pk_fma_f32 v[16:17], v[36:37], v[90:91], v[16:17] op_sel:[1,0,0]
	v_pk_fma_f32 v[36:37], v[210:211], v[104:105], v[8:9] op_sel_hi:[0,1,1]
	v_pk_fma_f32 v[8:9], v[10:11], v[72:73], v[238:239] op_sel_hi:[0,1,1]
	v_pk_fma_f32 v[4:5], v[22:23], v[82:83], v[4:5] op_sel_hi:[0,1,1]
	v_pk_fma_f32 v[8:9], v[22:23], v[80:81], v[8:9] op_sel_hi:[0,1,1]
	v_pk_fma_f32 v[4:5], v[34:35], v[78:79], v[4:5] op_sel_hi:[0,1,1]
	v_pk_fma_f32 v[8:9], v[34:35], v[76:77], v[8:9] op_sel_hi:[0,1,1]
	v_pk_fma_f32 v[4:5], v[46:47], v[90:91], v[4:5] op_sel_hi:[0,1,1]
	v_pk_fma_f32 v[8:9], v[46:47], v[88:89], v[8:9] op_sel_hi:[0,1,1]
	v_pk_fma_f32 v[4:5], v[162:163], v[86:87], v[4:5] op_sel_hi:[0,1,1]
	v_pk_fma_f32 v[8:9], v[162:163], v[84:85], v[8:9] op_sel_hi:[0,1,1]
	v_pk_fma_f32 v[4:5], v[198:199], v[98:99], v[4:5] op_sel_hi:[0,1,1]
	v_pk_fma_f32 v[8:9], v[198:199], v[96:97], v[8:9] op_sel_hi:[0,1,1]
	v_pk_fma_f32 v[4:5], v[206:207], v[94:95], v[4:5] op_sel_hi:[0,1,1]
	v_pk_fma_f32 v[220:221], v[160:161], v[86:87], v[220:221] op_sel_hi:[0,1,1]
	v_pk_fma_f32 v[222:223], v[160:161], v[84:85], v[222:223] op_sel_hi:[0,1,1]
	v_pk_fma_f32 v[8:9], v[206:207], v[92:93], v[8:9] op_sel_hi:[0,1,1]
	v_pk_fma_f32 v[160:161], v[214:215], v[106:107], v[4:5] op_sel_hi:[0,1,1]
	v_mov_b32_e32 v4, v7
	v_pk_fma_f32 v[216:217], v[156:157], v[86:87], v[216:217] op_sel_hi:[0,1,1]
	v_pk_fma_f32 v[218:219], v[156:157], v[84:85], v[218:219] op_sel_hi:[0,1,1]
	v_pk_fma_f32 v[16:17], v[156:157], v[86:87], v[16:17] op_sel:[1,0,0]
	v_pk_fma_f32 v[156:157], v[214:215], v[104:105], v[8:9] op_sel_hi:[0,1,1]
	v_pk_fma_f32 v[6:7], v[4:5], v[74:75], v[240:241] op_sel_hi:[0,1,1]
	v_pk_fma_f32 v[4:5], v[4:5], v[72:73], v[242:243] op_sel_hi:[0,1,1]
	v_mov_b32_e32 v8, v19
	v_pk_fma_f32 v[4:5], v[8:9], v[80:81], v[4:5] op_sel_hi:[0,1,1]
	v_pk_fma_f32 v[6:7], v[8:9], v[82:83], v[6:7] op_sel_hi:[0,1,1]
	v_mov_b32_e32 v8, v31
	v_pk_fma_f32 v[6:7], v[8:9], v[78:79], v[6:7] op_sel_hi:[0,1,1]
	v_pk_fma_f32 v[4:5], v[8:9], v[76:77], v[4:5] op_sel_hi:[0,1,1]
	v_mov_b32_e32 v8, v39
	v_pk_fma_f32 v[4:5], v[8:9], v[88:89], v[4:5] op_sel_hi:[0,1,1]
	v_pk_fma_f32 v[6:7], v[8:9], v[90:91], v[6:7] op_sel_hi:[0,1,1]
	v_mov_b32_e32 v8, v159
	v_pk_fma_f32 v[6:7], v[8:9], v[86:87], v[6:7] op_sel_hi:[0,1,1]
	v_pk_fma_f32 v[4:5], v[8:9], v[84:85], v[4:5] op_sel_hi:[0,1,1]
	v_mov_b32_e32 v8, v167
	v_pk_fma_f32 v[4:5], v[8:9], v[96:97], v[4:5] op_sel_hi:[0,1,1]
	v_pk_fma_f32 v[6:7], v[8:9], v[98:99], v[6:7] op_sel_hi:[0,1,1]
	v_mov_b32_e32 v8, v203
	v_pk_fma_f32 v[6:7], v[8:9], v[94:95], v[6:7] op_sel_hi:[0,1,1]
	v_pk_fma_f32 v[4:5], v[8:9], v[92:93], v[4:5] op_sel_hi:[0,1,1]
	v_mov_b32_e32 v8, v211
	v_pk_fma_f32 v[158:159], v[8:9], v[104:105], v[4:5] op_sel_hi:[0,1,1]
	v_mov_b32_e32 v4, v11
	v_pk_fma_f32 v[38:39], v[8:9], v[106:107], v[6:7] op_sel_hi:[0,1,1]
	v_pk_fma_f32 v[6:7], v[4:5], v[74:75], v[244:245] op_sel_hi:[0,1,1]
	v_pk_fma_f32 v[4:5], v[4:5], v[72:73], v[246:247] op_sel_hi:[0,1,1]
	v_mov_b32_e32 v8, v23
	v_pk_fma_f32 v[4:5], v[8:9], v[80:81], v[4:5] op_sel_hi:[0,1,1]
	v_pk_fma_f32 v[6:7], v[8:9], v[82:83], v[6:7] op_sel_hi:[0,1,1]
	v_mov_b32_e32 v8, v35
	v_pk_fma_f32 v[6:7], v[8:9], v[78:79], v[6:7] op_sel_hi:[0,1,1]
	v_pk_fma_f32 v[4:5], v[8:9], v[76:77], v[4:5] op_sel_hi:[0,1,1]
	v_mov_b32_e32 v8, v47
	v_pk_fma_f32 v[4:5], v[8:9], v[88:89], v[4:5] op_sel_hi:[0,1,1]
	v_pk_fma_f32 v[6:7], v[8:9], v[90:91], v[6:7] op_sel_hi:[0,1,1]
	v_mov_b32_e32 v8, v163
	s_add_u32 s4, s10, s42
	v_pk_fma_f32 v[6:7], v[8:9], v[86:87], v[6:7] op_sel_hi:[0,1,1]
	v_pk_fma_f32 v[4:5], v[8:9], v[84:85], v[4:5] op_sel_hi:[0,1,1]
	v_mov_b32_e32 v8, v199
	s_addc_u32 s5, s11, s43
	v_pk_fma_f32 v[4:5], v[8:9], v[96:97], v[4:5] op_sel_hi:[0,1,1]
	v_pk_fma_f32 v[6:7], v[8:9], v[98:99], v[6:7] op_sel_hi:[0,1,1]
	v_mov_b32_e32 v8, v207
	s_add_u32 s42, s4, s55
	v_pk_fma_f32 v[6:7], v[8:9], v[94:95], v[6:7] op_sel_hi:[0,1,1]
	v_pk_fma_f32 v[4:5], v[8:9], v[92:93], v[4:5] op_sel_hi:[0,1,1]
	v_mov_b32_e32 v8, v215
	s_addc_u32 s43, s5, 0
	v_pk_fma_f32 v[162:163], v[8:9], v[104:105], v[4:5] op_sel_hi:[0,1,1]
	v_lshl_add_u64 v[4:5], s[42:43], 0, v[168:169]
	v_pk_fma_f32 v[46:47], v[8:9], v[106:107], v[6:7] op_sel_hi:[0,1,1]
	v_add_co_u32_e64 v6, s[4:5], s13, v4
	v_pk_fma_f32 v[218:219], v[164:165], v[96:97], v[218:219] op_sel_hi:[0,1,1]
	s_nop 0
	v_addc_co_u32_e64 v7, s[4:5], 0, v5, s[4:5]
	global_load_dwordx4 v[80:83], v[6:7], off offset:-4096 nt
	global_load_dwordx4 v[76:79], v[6:7], off nt
	v_add_co_u32_e64 v6, s[4:5], s14, v4
	v_pk_fma_f32 v[216:217], v[164:165], v[98:99], v[216:217] op_sel_hi:[0,1,1]
	s_nop 0
	v_addc_co_u32_e64 v7, s[4:5], 0, v5, s[4:5]
	global_load_dwordx4 v[88:91], v[6:7], off offset:-4096 nt
	global_load_dwordx4 v[84:87], v[6:7], off nt
	v_add_co_u32_e64 v6, s[4:5], s15, v4
	v_pk_fma_f32 v[222:223], v[196:197], v[96:97], v[222:223] op_sel_hi:[0,1,1]
	v_pk_fma_f32 v[220:221], v[196:197], v[98:99], v[220:221] op_sel_hi:[0,1,1]
	v_pk_fma_f32 v[16:17], v[164:165], v[98:99], v[16:17] op_sel:[1,0,0]
	v_addc_co_u32_e64 v7, s[4:5], 0, v5, s[4:5]
	v_pk_fma_f32 v[216:217], v[200:201], v[94:95], v[216:217] op_sel_hi:[0,1,1]
	v_pk_fma_f32 v[218:219], v[200:201], v[92:93], v[218:219] op_sel_hi:[0,1,1]
	v_pk_fma_f32 v[220:221], v[204:205], v[94:95], v[220:221] op_sel_hi:[0,1,1]
	v_pk_fma_f32 v[222:223], v[204:205], v[92:93], v[222:223] op_sel_hi:[0,1,1]
	v_pk_fma_f32 v[16:17], v[200:201], v[94:95], v[16:17] op_sel:[1,0,0]
	v_add_co_u32_e64 v4, s[4:5], s26, v4
	v_pk_fma_f32 v[218:219], v[208:209], v[104:105], v[218:219] op_sel_hi:[0,1,1]
	v_pk_fma_f32 v[216:217], v[208:209], v[106:107], v[216:217] op_sel_hi:[0,1,1]
	v_pk_fma_f32 v[222:223], v[212:213], v[104:105], v[222:223] op_sel_hi:[0,1,1]
	v_pk_fma_f32 v[220:221], v[212:213], v[106:107], v[220:221] op_sel_hi:[0,1,1]
	v_pk_fma_f32 v[16:17], v[208:209], v[106:107], v[16:17] op_sel:[1,0,0]
	global_load_dwordx4 v[96:99], v[6:7], off offset:-4096 nt
	global_load_dwordx4 v[92:95], v[6:7], off nt
	v_addc_co_u32_e64 v5, s[4:5], 0, v5, s[4:5]
	global_load_dwordx4 v[72:75], v168, s[42:43] nt
	global_load_dwordx4 v[104:107], v[4:5], off nt
	v_sub_f32_e32 v4, v192, v172
	v_exp_f32_e32 v18, v4
	v_sub_f32_e32 v4, v193, v178
	v_exp_f32_e32 v19, v4
	v_sub_f32_e32 v4, v194, v180
	v_exp_f32_e32 v164, v4
	v_sub_f32_e32 v4, v195, v170
	v_exp_f32_e32 v165, v4
	v_pk_fma_f32 v[4:5], v[174:175], v[152:153], v[112:113]
	v_pk_fma_f32 v[6:7], v[176:177], v[154:155], v[114:115]
	v_readlane_b32 s4, v18, 0
	v_pk_fma_f32 v[174:175], v[4:5], v[18:19], v[148:149]
	v_pk_fma_f32 v[176:177], v[6:7], v[164:165], v[150:151]
	v_readlane_b32 s16, v18, 16
	v_pk_mul_f32 v[6:7], v[216:217], s[4:5] op_sel_hi:[1,0]
	v_pk_mul_f32 v[4:5], v[218:219], s[4:5] op_sel_hi:[1,0]
	v_readlane_b32 s4, v19, 0
	v_pk_mul_f32 v[10:11], v[220:221], s[16:17] op_sel_hi:[1,0]
	v_pk_mul_f32 v[8:9], v[222:223], s[16:17] op_sel_hi:[1,0]
	v_readlane_b32 s16, v19, 16
	v_pk_mul_f32 v[18:19], v[16:17], s[4:5] op_sel_hi:[1,0]
	v_pk_mul_f32 v[16:17], v[28:29], s[4:5] op_sel_hi:[1,0]
	v_readlane_b32 s4, v164, 0
	v_pk_mul_f32 v[22:23], v[32:33], s[16:17] op_sel_hi:[1,0]
	v_pk_mul_f32 v[20:21], v[20:21], s[16:17] op_sel_hi:[1,0]
	v_readlane_b32 s16, v164, 16
	v_pk_mul_f32 v[30:31], v[44:45], s[4:5] op_sel_hi:[1,0]
	v_pk_mul_f32 v[28:29], v[36:37], s[4:5] op_sel_hi:[1,0]
	v_readlane_b32 s4, v165, 0
	s_waitcnt lgkmcnt(0)
	v_pk_mul_f32 v[34:35], v[160:161], s[16:17] op_sel_hi:[1,0]
	v_pk_mul_f32 v[32:33], v[156:157], s[16:17] op_sel_hi:[1,0]
	v_readlane_b32 s16, v165, 16
	v_pk_mul_f32 v[38:39], v[38:39], s[4:5] op_sel_hi:[1,0]
	v_pk_mul_f32 v[36:37], v[158:159], s[4:5] op_sel_hi:[1,0]
	s_add_i32 s4, s53, 2
	s_add_i32 s51, s51, 32
	v_pk_mul_f32 v[46:47], v[46:47], s[16:17] op_sel_hi:[1,0]
	v_pk_mul_f32 v[44:45], v[162:163], s[16:17] op_sel_hi:[1,0]
	s_cmp_gt_u32 s53, 29
	s_cbranch_scc1 .LBB0_437
	s_mov_b32 s53, s4
	s_branch .LBB0_429

.LBB0_552:
	v_mbcnt_lo_u32_b32 v0, -1, 0
	v_mbcnt_hi_u32_b32 v0, -1, v0
	v_mov_b32_e32 v182, 0x3eb8aa3b
	v_add_u32_e32 v188, s73, v0
	s_lshl_b32 s88, s93, 13
	s_add_u32 s88, s88, 0x13000
	s_add_u32 s89, s88, 0x1000
	s_cmp_eq_u32 s93, 6
	s_cselect_b32 s89, 0x20200, s89
	s_cmp_eq_u32 s93, 7
	s_cselect_b32 s88, 0x21200, s88
	s_cselect_b32 s89, 0x22200, s89
	v_lshlrev_b32_e32 v249, 4, v0
	v_add_u32_e32 v250, s89, v249
	v_add_u32_e32 v249, s88, v249
	s_nop 0
	v_readfirstlane_b32 s6, v188
	s_ashr_i32 s35, s6, 6
	s_and_b32 s24, s35, 3
	s_cmp_lt_i32 s24, 1
	s_cbranch_scc1 .LBB0_557
	s_cmp_eq_u32 s24, 1
	s_cbranch_scc1 .LBB0_555
	s_cmp_eq_u32 s24, 2
	s_cselect_b64 vcc, -1, 0
	v_cndmask_b32_e32 v182, v186, v187, vcc
	s_cbranch_execz .LBB0_556
	s_branch .LBB0_557

.LBB0_565:
	s_or_b64 exec, exec, s[22:23]
	s_and_b32 s24, s31, 7
	s_lshl_b32 s6, s24, 3
	s_and_b32 s25, s35, -4
	s_add_i32 s25, s25, s6
	s_lshl_b32 s6, s43, 6
	s_add_i32 s6, s25, s6
	s_ashr_i32 s7, s6, 31
	s_lshl_b32 s22, s35, 10
	s_lshl_b64 s[6:7], s[6:7], 2
	s_add_u32 s6, s12, s6
	s_addc_u32 s7, s13, s7
	s_waitcnt vmcnt(1)
	v_cvt_pk_bf16_f32 v60, v0, v1
	v_cvt_pk_bf16_f32 v61, v2, v3
	s_waitcnt vmcnt(0)
	v_cvt_pk_bf16_f32 v62, v4, v5
	v_cvt_pk_bf16_f32 v63, v6, v7
	global_load_dwordx4 v[0:3], v169, s[6:7]
	v_and_b32_e32 v9, 63, v188
	v_and_b32_e32 v13, 31, v188
	v_lshrrev_b32_e32 v16, 5, v9
	v_lshlrev_b32_e32 v171, 2, v13
	v_lshlrev_b32_e32 v4, 9, v16
	v_or3_b32 v8, s16, v4, v171
	s_add_i32 s16, s22, 0
	v_lshlrev_b32_e32 v168, 2, v8
	v_mov_b32_e32 v174, 0
	s_mov_b32 s51, 0
	v_or_b32_e32 v179, 0xffffe000, v12
	v_mov_b32_e32 v184, v182
	v_mov_b32_e32 v185, v182
	v_mov_b32_e32 v172, 0xf149f2ca
	s_mov_b32 s53, 0
	v_mov_b32_e32 v175, v174
	v_mov_b32_e32 v176, v174
	v_mov_b32_e32 v177, v174
	v_mov_b32_e32 v178, 0xf149f2ca
	v_mov_b32_e32 v180, 0xf149f2ca
	v_mov_b32_e32 v170, 0xf149f2ca
	s_waitcnt vmcnt(0)
	v_readfirstlane_b32 s22, v0
	s_ashr_i32 s23, s22, 31
	s_lshl_b64 s[6:7], s[22:23], 18
	s_add_u32 s40, s8, s6
	s_addc_u32 s41, s9, s7
	v_lshl_add_u64 v[4:5], s[40:41], 0, v[168:169]
	v_add_co_u32_e32 v6, vcc, s14, v4
	s_add_u32 s6, s10, s6
	s_nop 0
	v_addc_co_u32_e32 v7, vcc, 0, v5, vcc
	v_add_co_u32_e32 v10, vcc, s15, v4
	s_addc_u32 s7, s11, s7
	s_nop 0
	v_addc_co_u32_e32 v11, vcc, 0, v5, vcc
	v_add_co_u32_e32 v14, vcc, s26, v4
	v_readfirstlane_b32 s45, v1
	s_nop 0
	v_addc_co_u32_e32 v15, vcc, 0, v5, vcc
	v_add_co_u32_e32 v4, vcc, s27, v4
	v_readfirstlane_b32 s47, v2
	s_nop 0
	v_addc_co_u32_e32 v5, vcc, 0, v5, vcc
	global_load_dwordx4 v[140:143], v[6:7], off offset:-4096 nt
	global_load_dwordx4 v[136:139], v[6:7], off nt
	global_load_dwordx4 v[132:135], v[10:11], off offset:-4096 nt
	global_load_dwordx4 v[128:131], v[10:11], off nt
	global_load_dwordx4 v[124:127], v[14:15], off offset:-4096 nt
	global_load_dwordx4 v[120:123], v[14:15], off nt
	global_load_dwordx4 v[116:119], v[4:5], off nt
	v_lshl_add_u64 v[4:5], s[6:7], 0, v[168:169]
	v_add_co_u32_e32 v6, vcc, s14, v4
	global_load_dwordx4 v[144:147], v168, s[40:41] nt
	s_add_u32 s80, s40, 0x8000
	s_addc_u32 s81, s41, 0
	s_mov_b32 m0, s88
	s_nop 0
	global_load_lds_dwordx4 v168, s[80:81] nt
	s_add_u32 s80, s80, 0x1000
	s_addc_u32 s81, s81, 0
	s_add_u32 m0, m0, 0x400
	s_nop 0
	global_load_lds_dwordx4 v168, s[80:81] nt
	s_add_u32 s80, s80, 0x1000
	s_addc_u32 s81, s81, 0
	s_add_u32 m0, m0, 0x400
	s_nop 0
	global_load_lds_dwordx4 v168, s[80:81] nt
	s_add_u32 s80, s80, 0x1000
	s_addc_u32 s81, s81, 0
	s_add_u32 m0, m0, 0x400
	s_nop 0
	global_load_lds_dwordx4 v168, s[80:81] nt
	s_add_u32 s80, s80, 0x1000
	s_addc_u32 s81, s81, 0
	s_mov_b32 m0, s89
	s_nop 0
	global_load_lds_dwordx4 v168, s[80:81] nt
	s_add_u32 s80, s80, 0x1000
	s_addc_u32 s81, s81, 0
	s_add_u32 m0, m0, 0x400
	s_nop 0
	global_load_lds_dwordx4 v168, s[80:81] nt
	s_add_u32 s80, s80, 0x1000
	s_addc_u32 s81, s81, 0
	s_add_u32 m0, m0, 0x400
	s_nop 0
	global_load_lds_dwordx4 v168, s[80:81] nt
	s_add_u32 s80, s80, 0x1000
	s_addc_u32 s81, s81, 0
	s_add_u32 m0, m0, 0x400
	s_nop 0
	global_load_lds_dwordx4 v168, s[80:81] nt
	global_load_dwordx4 v[72:75], v168, s[6:7] nt
	v_addc_co_u32_e32 v7, vcc, 0, v5, vcc
	v_add_co_u32_e32 v10, vcc, s15, v4
	s_mul_i32 s6, s35, 0x1100
	s_nop 0
	v_addc_co_u32_e32 v11, vcc, 0, v5, vcc
	v_add_co_u32_e32 v14, vcc, s26, v4
	s_add_i32 s23, s6, 0
	s_nop 0
	v_addc_co_u32_e32 v15, vcc, 0, v5, vcc
	v_add_co_u32_e32 v4, vcc, s27, v4
	v_mov_b32_e32 v0, s23
	s_nop 0
	v_addc_co_u32_e32 v5, vcc, 0, v5, vcc
	global_load_dwordx4 v[80:83], v[6:7], off offset:-4096 nt
	global_load_dwordx4 v[76:79], v[6:7], off nt
	global_load_dwordx4 v[88:91], v[10:11], off offset:-4096 nt
	global_load_dwordx4 v[84:87], v[10:11], off nt
	global_load_dwordx4 v[96:99], v[14:15], off offset:-4096 nt
	global_load_dwordx4 v[92:95], v[14:15], off nt
	global_load_dwordx4 v[104:107], v[4:5], off nt
	v_lshl_add_u32 v1, v13, 3, s23
	v_cmp_gt_u32_e32 vcc, 32, v9
	v_and_b32_e32 v9, 32, v188
	v_mul_u32_u24_e32 v10, 0x110, v16
	v_mov_b32_e32 v6, v169
	v_mov_b32_e32 v7, v169
	v_readfirstlane_b32 s49, v3
	v_mad_u32_u24 v0, v12, s28, v0
	v_and_b32_e32 v2, 48, v188
	v_lshl_add_u32 v3, v12, 5, s16
	v_mov_b32_e32 v4, v169
	v_mov_b32_e32 v5, v169
	v_lshlrev_b32_e32 v168, 2, v8
	v_add_u32_e32 v181, v1, v10
	v_add_u32_e32 v173, s16, v9
	v_mov_b64_e32 v[18:19], v[6:7]
	v_mov_b64_e32 v[30:31], v[6:7]
	v_mov_b64_e32 v[38:39], v[6:7]
	v_mov_b64_e32 v[10:11], v[6:7]
	v_mov_b64_e32 v[22:23], v[6:7]
	v_mov_b64_e32 v[34:35], v[6:7]
	v_mov_b64_e32 v[46:47], v[6:7]
	v_add_u32_e32 v190, v0, v2
	v_add_u32_e32 v191, v3, v2
	v_mov_b64_e32 v[16:17], v[4:5]
	v_mov_b64_e32 v[28:29], v[4:5]
	v_mov_b64_e32 v[36:37], v[4:5]
	v_mov_b64_e32 v[8:9], v[4:5]
	v_mov_b64_e32 v[20:21], v[4:5]
	v_mov_b64_e32 v[32:33], v[4:5]
	v_mov_b64_e32 v[44:45], v[4:5]
	s_waitcnt vmcnt(16)
.LBB0_566:
	s_lshr_b32 s42, s53, 3
	s_cmp_eq_u32 s42, 2
	s_cselect_b32 s6, s47, s49
	s_cmp_eq_u32 s42, 1
	s_waitcnt vmcnt(24)
	v_cvt_pk_bf16_f32 v112, v144, v145
	v_cvt_pk_bf16_f32 v113, v146, v147
	s_cselect_b32 s6, s45, s6
	s_cmp_lt_u32 s53, 8
	ds_write_b64 v181, v[112:113] offset:43008
	v_cvt_pk_bf16_f32 v112, v140, v141
	v_cvt_pk_bf16_f32 v113, v142, v143
	s_cselect_b32 s6, s22, s6
	ds_write_b64 v181, v[112:113] offset:43552
	v_cvt_pk_bf16_f32 v112, v136, v137
	v_cvt_pk_bf16_f32 v113, v138, v139
	s_ashr_i32 s7, s6, 31
	s_and_b32 s46, s51, 0x60
	ds_write_b64 v181, v[112:113] offset:44096
	v_cvt_pk_bf16_f32 v112, v132, v133
	v_cvt_pk_bf16_f32 v113, v134, v135
	s_or_b32 s16, s46, 16
	s_lshl_b64 s[40:41], s[6:7], 18
	ds_write_b64 v181, v[112:113] offset:44640
	v_cvt_pk_bf16_f32 v112, v128, v129
	v_cvt_pk_bf16_f32 v113, v130, v131
	s_add_u32 s6, s8, s40
	ds_write_b64 v181, v[112:113] offset:45184
	v_cvt_pk_bf16_f32 v112, v124, v125
	v_cvt_pk_bf16_f32 v113, v126, v127
	s_addc_u32 s7, s9, s41
	s_lshl_b32 s44, s16, 11
	ds_write_b64 v181, v[112:113] offset:45728
	v_cvt_pk_bf16_f32 v112, v120, v121
	v_cvt_pk_bf16_f32 v113, v122, v123
	s_add_u32 s54, s6, s44
	ds_write_b64 v181, v[112:113] offset:46272
	v_cvt_pk_bf16_f32 v112, v116, v117
	v_cvt_pk_bf16_f32 v113, v118, v119
	s_addc_u32 s55, s7, 0
	ds_write_b64 v181, v[112:113] offset:46816
	v_mov_b32_e32 v183, v182
	s_add_i32 s84, s53, 2
	s_min_u32 s84, s84, 31
	s_lshr_b32 s85, s84, 3
	s_cmp_eq_u32 s85, 2
	s_cselect_b32 s86, s47, s49
	s_cmp_eq_u32 s85, 1
	s_cselect_b32 s86, s45, s86
	s_cmp_eq_u32 s85, 0
	s_cselect_b32 s86, s22, s86
	s_ashr_i32 s87, s86, 31
	s_lshl_b64 s[86:87], s[86:87], 18
	s_and_b32 s85, s84, 7
	s_lshl_b32 s85, s85, 15
	s_add_u32 s86, s86, s85
	s_addc_u32 s87, s87, 0
	s_add_u32 s86, s86, 0x1000
	s_addc_u32 s87, s87, 0
	s_add_u32 s80, s8, s86
	s_addc_u32 s81, s9, s87
	global_load_dwordx4 v[144:147], v168, s[80:81] offset:-4096 nt
	global_load_dwordx4 v[140:143], v168, s[80:81] nt
	s_add_u32 s80, s80, 0x2000
	s_addc_u32 s81, s81, 0
	global_load_dwordx4 v[136:139], v168, s[80:81] offset:-4096 nt
	global_load_dwordx4 v[132:135], v168, s[80:81] nt
	s_add_u32 s80, s80, 0x2000
	s_addc_u32 s81, s81, 0
	global_load_dwordx4 v[128:131], v168, s[80:81] offset:-4096 nt
	global_load_dwordx4 v[124:127], v168, s[80:81] nt
	s_add_u32 s80, s80, 0x2000
	s_addc_u32 s81, s81, 0
	global_load_dwordx4 v[120:123], v168, s[80:81] offset:-4096 nt
	global_load_dwordx4 v[116:119], v168, s[80:81] nt
	s_or_b32 s6, s42, s25
	s_lshl_b32 s42, s6, 7
	s_or_b32 s6, s42, s46
	v_add_u32_e32 v112, s6, v179
	v_add_u32_e32 v113, -1, v112
	v_add_u32_e32 v114, -2, v112
	v_add_u32_e32 v115, -3, v112
	s_waitcnt lgkmcnt(0)
	v_cvt_f32_i32_e32 v152, v112
	v_cvt_f32_i32_e32 v153, v113
	v_cvt_f32_i32_e32 v155, v115
	v_cvt_f32_i32_e32 v154, v114
	ds_read_b128 v[112:115], v190 offset:43008
	ds_read_b128 v[148:151], v190 offset:43072
	v_pk_mul_f32 v[152:153], v[184:185], v[152:153]
	v_pk_mul_f32 v[154:155], v[182:183], v[154:155]
	s_waitcnt lgkmcnt(1)
	s_nop 0
	v_mfma_f32_16x16x32_bf16 v[112:115], v[24:27], v[112:115], v[152:155]
	s_waitcnt lgkmcnt(0)
	v_mfma_f32_16x16x32_bf16 v[112:115], v[48:51], v[148:151], v[112:115]
	ds_read_b128 v[148:151], v190 offset:43136
	ds_read_b128 v[152:155], v190 offset:43200
	s_waitcnt lgkmcnt(1)
	v_mfma_f32_16x16x32_bf16 v[112:115], v[52:55], v[148:151], v[112:115]
	s_waitcnt lgkmcnt(0)
	v_mfma_f32_16x16x32_bf16 v[112:115], v[60:63], v[152:155], v[112:115]
	s_nop 7
	v_mov_b32_dpp v148, v112 quad_perm:[1,0,3,2] row_mask:0xf bank_mask:0xf bound_ctrl:1
	v_max_f32_e32 v149, v112, v112
	v_max_f32_e32 v148, v148, v148
	v_max_f32_e32 v148, v149, v148
	s_nop 1
	v_mov_b32_dpp v149, v148 quad_perm:[2,3,0,1] row_mask:0xf bank_mask:0xf bound_ctrl:1
	v_max_f32_e32 v149, v149, v149
	v_max_f32_e32 v148, v148, v149
	s_nop 1
	v_mov_b32_dpp v149, v148 row_half_mirror row_mask:0xf bank_mask:0xf bound_ctrl:1
	v_max_f32_e32 v149, v149, v149
	v_max_f32_e32 v148, v148, v149
	s_nop 1
	v_mov_b32_dpp v149, v148 row_ror:8 row_mask:0xf bank_mask:0xf bound_ctrl:1
	v_max3_f32 v192, v172, v148, v149
	v_mov_b32_dpp v148, v113 quad_perm:[1,0,3,2] row_mask:0xf bank_mask:0xf bound_ctrl:1
	v_max_f32_e32 v149, v113, v113
	v_max_f32_e32 v148, v148, v148
	v_max_f32_e32 v148, v149, v148
	v_sub_f32_e32 v112, v112, v192
	v_exp_f32_e32 v112, v112
	v_mov_b32_dpp v149, v148 quad_perm:[2,3,0,1] row_mask:0xf bank_mask:0xf bound_ctrl:1
	v_max_f32_e32 v149, v149, v149
	v_max_f32_e32 v148, v148, v149
	s_nop 1
	v_mov_b32_dpp v149, v148 row_half_mirror row_mask:0xf bank_mask:0xf bound_ctrl:1
	v_max_f32_e32 v149, v149, v149
	v_max_f32_e32 v148, v148, v149
	s_nop 1
	v_mov_b32_dpp v149, v148 row_ror:8 row_mask:0xf bank_mask:0xf bound_ctrl:1
	v_max3_f32 v193, v178, v148, v149
	v_mov_b32_dpp v148, v114 quad_perm:[1,0,3,2] row_mask:0xf bank_mask:0xf bound_ctrl:1
	v_max_f32_e32 v149, v114, v114
	v_max_f32_e32 v148, v148, v148
	v_max_f32_e32 v148, v149, v148
	v_sub_f32_e32 v113, v113, v193
	v_exp_f32_e32 v113, v113
	v_mov_b32_dpp v149, v148 quad_perm:[2,3,0,1] row_mask:0xf bank_mask:0xf bound_ctrl:1
	v_max_f32_e32 v149, v149, v149
	v_max_f32_e32 v148, v148, v149
	s_nop 1
	v_mov_b32_dpp v149, v148 row_half_mirror row_mask:0xf bank_mask:0xf bound_ctrl:1
	v_max_f32_e32 v149, v149, v149
	v_max_f32_e32 v148, v148, v149
	s_nop 1
	v_mov_b32_dpp v149, v148 row_ror:8 row_mask:0xf bank_mask:0xf bound_ctrl:1
	v_max3_f32 v194, v180, v148, v149
	v_mov_b32_dpp v148, v115 quad_perm:[1,0,3,2] row_mask:0xf bank_mask:0xf bound_ctrl:1
	v_max_f32_e32 v149, v115, v115
	v_max_f32_e32 v148, v148, v148
	v_max_f32_e32 v148, v149, v148
	v_sub_f32_e32 v114, v114, v194
	v_exp_f32_e32 v114, v114
	v_mov_b32_dpp v149, v148 quad_perm:[2,3,0,1] row_mask:0xf bank_mask:0xf bound_ctrl:1
	v_max_f32_e32 v149, v149, v149
	v_max_f32_e32 v148, v148, v149
	s_nop 1
	v_mov_b32_dpp v149, v148 row_half_mirror row_mask:0xf bank_mask:0xf bound_ctrl:1
	v_max_f32_e32 v149, v149, v149
	v_max_f32_e32 v148, v148, v149
	s_nop 1
	v_mov_b32_dpp v149, v148 row_ror:8 row_mask:0xf bank_mask:0xf bound_ctrl:1
	v_max3_f32 v195, v170, v148, v149
	v_sub_f32_e32 v115, v115, v195
	v_exp_f32_e32 v115, v115
	s_and_saveexec_b64 s[6:7], vcc
	ds_write_b128 v191, v[112:115] offset:34816
	s_or_b64 exec, exec, s[6:7]
	s_cmp_eq_u32 s53, 0
	s_cbranch_scc1 .LBB0_570
	s_waitcnt vmcnt(24)
	ds_read_b128 v[196:199], v173 offset:35328
	ds_read_b128 v[200:203], v173 offset:35344
	ds_read_b128 v[204:207], v173 offset:35392
	ds_read_b128 v[208:211], v173 offset:35408
	ds_read_b128 v[212:215], v173 offset:35456
	ds_read_b128 v[216:219], v173 offset:35472
	ds_read_b128 v[220:223], v173 offset:35520
	ds_read_b128 v[164:167], v173 offset:35536
	ds_read_b128 v[224:227], v173 offset:35584
	ds_read_b128 v[160:163], v173 offset:35600
	ds_read_b128 v[228:231], v173 offset:35648
	ds_read_b128 v[156:159], v173 offset:35664
	ds_read_b128 v[232:235], v173 offset:35712
	ds_read_b128 v[152:155], v173 offset:35728
	ds_read_b128 v[236:239], v173 offset:35776
	ds_read_b128 v[148:151], v173 offset:35792
	s_waitcnt lgkmcnt(14)
	v_pk_fma_f32 v[10:11], v[200:201], v[110:111], v[10:11] op_sel_hi:[0,1,1]
	v_pk_fma_f32 v[8:9], v[200:201], v[108:109], v[8:9] op_sel_hi:[0,1,1]
	v_pk_fma_f32 v[22:23], v[200:201], v[110:111], v[22:23] op_sel:[1,0,0]
	v_pk_fma_f32 v[20:21], v[200:201], v[108:109], v[20:21] op_sel:[1,0,0]
	s_waitcnt lgkmcnt(12)
	v_pk_fma_f32 v[10:11], v[208:209], v[102:103], v[10:11] op_sel_hi:[0,1,1]
	v_pk_fma_f32 v[8:9], v[208:209], v[100:101], v[8:9] op_sel_hi:[0,1,1]
	v_pk_fma_f32 v[22:23], v[208:209], v[102:103], v[22:23] op_sel:[1,0,0]
	v_pk_fma_f32 v[20:21], v[208:209], v[100:101], v[20:21] op_sel:[1,0,0]
	s_waitcnt lgkmcnt(10)
	v_pk_fma_f32 v[10:11], v[216:217], v[70:71], v[10:11] op_sel_hi:[0,1,1]
	v_pk_fma_f32 v[8:9], v[216:217], v[68:69], v[8:9] op_sel_hi:[0,1,1]
	v_pk_fma_f32 v[22:23], v[216:217], v[70:71], v[22:23] op_sel:[1,0,0]
	v_pk_fma_f32 v[20:21], v[216:217], v[68:69], v[20:21] op_sel:[1,0,0]
	s_waitcnt lgkmcnt(8)
	v_pk_fma_f32 v[10:11], v[164:165], v[66:67], v[10:11] op_sel_hi:[0,1,1]
	v_pk_fma_f32 v[8:9], v[164:165], v[64:65], v[8:9] op_sel_hi:[0,1,1]
	v_pk_fma_f32 v[22:23], v[164:165], v[66:67], v[22:23] op_sel:[1,0,0]
	v_pk_fma_f32 v[20:21], v[164:165], v[64:65], v[20:21] op_sel:[1,0,0]
	s_waitcnt lgkmcnt(6)
	v_pk_fma_f32 v[10:11], v[160:161], v[58:59], v[10:11] op_sel_hi:[0,1,1]
	v_pk_fma_f32 v[8:9], v[160:161], v[56:57], v[8:9] op_sel_hi:[0,1,1]
	v_pk_fma_f32 v[22:23], v[160:161], v[58:59], v[22:23] op_sel:[1,0,0]
	v_pk_fma_f32 v[20:21], v[160:161], v[56:57], v[20:21] op_sel:[1,0,0]
	s_waitcnt lgkmcnt(4)
	v_pk_fma_f32 v[10:11], v[156:157], v[42:43], v[10:11] op_sel_hi:[0,1,1]
	v_pk_fma_f32 v[8:9], v[156:157], v[40:41], v[8:9] op_sel_hi:[0,1,1]
	v_pk_fma_f32 v[22:23], v[156:157], v[42:43], v[22:23] op_sel:[1,0,0]
	v_pk_fma_f32 v[20:21], v[156:157], v[40:41], v[20:21] op_sel:[1,0,0]
	s_waitcnt lgkmcnt(2)
	v_pk_fma_f32 v[10:11], v[152:153], v[14:15], v[10:11] op_sel_hi:[0,1,1]
	v_pk_fma_f32 v[8:9], v[152:153], v[12:13], v[8:9] op_sel_hi:[0,1,1]
	v_pk_fma_f32 v[22:23], v[152:153], v[14:15], v[22:23] op_sel:[1,0,0]
	v_pk_fma_f32 v[20:21], v[152:153], v[12:13], v[20:21] op_sel:[1,0,0]
	s_waitcnt lgkmcnt(0)
	v_pk_fma_f32 v[10:11], v[148:149], v[2:3], v[10:11] op_sel_hi:[0,1,1]
	v_pk_fma_f32 v[8:9], v[148:149], v[0:1], v[8:9] op_sel_hi:[0,1,1]
	v_pk_fma_f32 v[22:23], v[148:149], v[2:3], v[22:23] op_sel:[1,0,0]
	v_pk_fma_f32 v[20:21], v[148:149], v[0:1], v[20:21] op_sel:[1,0,0]
	v_mov_b32_e32 v148, v199
	v_pk_fma_f32 v[38:39], v[148:149], v[110:111], v[38:39] op_sel_hi:[0,1,1]
	v_pk_fma_f32 v[36:37], v[148:149], v[108:109], v[36:37] op_sel_hi:[0,1,1]
	v_mov_b32_e32 v148, v207
	v_pk_fma_f32 v[38:39], v[148:149], v[102:103], v[38:39] op_sel_hi:[0,1,1]
	v_pk_fma_f32 v[36:37], v[148:149], v[100:101], v[36:37] op_sel_hi:[0,1,1]
	v_mov_b32_e32 v148, v215
	v_pk_fma_f32 v[38:39], v[148:149], v[70:71], v[38:39] op_sel_hi:[0,1,1]
	v_pk_fma_f32 v[36:37], v[148:149], v[68:69], v[36:37] op_sel_hi:[0,1,1]
	v_mov_b32_e32 v148, v223
	v_pk_fma_f32 v[38:39], v[148:149], v[66:67], v[38:39] op_sel_hi:[0,1,1]
	v_pk_fma_f32 v[36:37], v[148:149], v[64:65], v[36:37] op_sel_hi:[0,1,1]
	v_mov_b32_e32 v148, v227
	v_pk_fma_f32 v[38:39], v[148:149], v[58:59], v[38:39] op_sel_hi:[0,1,1]
	v_pk_fma_f32 v[36:37], v[148:149], v[56:57], v[36:37] op_sel_hi:[0,1,1]
	v_mov_b32_e32 v148, v231
	v_pk_fma_f32 v[38:39], v[148:149], v[42:43], v[38:39] op_sel_hi:[0,1,1]
	v_pk_fma_f32 v[36:37], v[148:149], v[40:41], v[36:37] op_sel_hi:[0,1,1]
	v_mov_b32_e32 v148, v235
	v_pk_fma_f32 v[38:39], v[148:149], v[14:15], v[38:39] op_sel_hi:[0,1,1]
	v_pk_fma_f32 v[36:37], v[148:149], v[12:13], v[36:37] op_sel_hi:[0,1,1]
	v_mov_b32_e32 v148, v239
	v_pk_fma_f32 v[38:39], v[148:149], v[2:3], v[38:39] op_sel_hi:[0,1,1]
	v_pk_fma_f32 v[36:37], v[148:149], v[0:1], v[36:37] op_sel_hi:[0,1,1]
	v_mov_b32_e32 v148, v203
	v_pk_fma_f32 v[6:7], v[196:197], v[110:111], v[6:7] op_sel_hi:[0,1,1]
	v_pk_fma_f32 v[4:5], v[196:197], v[108:109], v[4:5] op_sel_hi:[0,1,1]
	v_pk_fma_f32 v[18:19], v[196:197], v[110:111], v[18:19] op_sel:[1,0,0]
	v_pk_fma_f32 v[16:17], v[196:197], v[108:109], v[16:17] op_sel:[1,0,0]
	v_pk_fma_f32 v[30:31], v[198:199], v[110:111], v[30:31] op_sel_hi:[0,1,1]
	v_pk_fma_f32 v[28:29], v[198:199], v[108:109], v[28:29] op_sel_hi:[0,1,1]
	v_pk_fma_f32 v[34:35], v[202:203], v[110:111], v[34:35] op_sel_hi:[0,1,1]
	v_pk_fma_f32 v[32:33], v[202:203], v[108:109], v[32:33] op_sel_hi:[0,1,1]
	v_pk_fma_f32 v[46:47], v[148:149], v[110:111], v[46:47] op_sel_hi:[0,1,1]
	v_pk_fma_f32 v[44:45], v[148:149], v[108:109], v[44:45] op_sel_hi:[0,1,1]
	v_mov_b32_e32 v108, v211
	v_pk_fma_f32 v[6:7], v[204:205], v[102:103], v[6:7] op_sel_hi:[0,1,1]
	v_pk_fma_f32 v[4:5], v[204:205], v[100:101], v[4:5] op_sel_hi:[0,1,1]
	v_pk_fma_f32 v[18:19], v[204:205], v[102:103], v[18:19] op_sel:[1,0,0]
	v_pk_fma_f32 v[16:17], v[204:205], v[100:101], v[16:17] op_sel:[1,0,0]
	v_pk_fma_f32 v[30:31], v[206:207], v[102:103], v[30:31] op_sel_hi:[0,1,1]
	v_pk_fma_f32 v[28:29], v[206:207], v[100:101], v[28:29] op_sel_hi:[0,1,1]
	v_pk_fma_f32 v[34:35], v[210:211], v[102:103], v[34:35] op_sel_hi:[0,1,1]
	v_pk_fma_f32 v[32:33], v[210:211], v[100:101], v[32:33] op_sel_hi:[0,1,1]
	v_pk_fma_f32 v[46:47], v[108:109], v[102:103], v[46:47] op_sel_hi:[0,1,1]
	v_pk_fma_f32 v[44:45], v[108:109], v[100:101], v[44:45] op_sel_hi:[0,1,1]
	v_mov_b32_e32 v100, v219
	v_pk_fma_f32 v[6:7], v[212:213], v[70:71], v[6:7] op_sel_hi:[0,1,1]
	v_pk_fma_f32 v[4:5], v[212:213], v[68:69], v[4:5] op_sel_hi:[0,1,1]
	v_pk_fma_f32 v[18:19], v[212:213], v[70:71], v[18:19] op_sel:[1,0,0]
	v_pk_fma_f32 v[16:17], v[212:213], v[68:69], v[16:17] op_sel:[1,0,0]
	v_pk_fma_f32 v[30:31], v[214:215], v[70:71], v[30:31] op_sel_hi:[0,1,1]
	v_pk_fma_f32 v[28:29], v[214:215], v[68:69], v[28:29] op_sel_hi:[0,1,1]
	v_pk_fma_f32 v[34:35], v[218:219], v[70:71], v[34:35] op_sel_hi:[0,1,1]
	v_pk_fma_f32 v[32:33], v[218:219], v[68:69], v[32:33] op_sel_hi:[0,1,1]
	v_pk_fma_f32 v[46:47], v[100:101], v[70:71], v[46:47] op_sel_hi:[0,1,1]
	v_pk_fma_f32 v[44:45], v[100:101], v[68:69], v[44:45] op_sel_hi:[0,1,1]
	v_mov_b32_e32 v68, v167
	v_pk_fma_f32 v[6:7], v[220:221], v[66:67], v[6:7] op_sel_hi:[0,1,1]
	v_pk_fma_f32 v[4:5], v[220:221], v[64:65], v[4:5] op_sel_hi:[0,1,1]
	v_pk_fma_f32 v[18:19], v[220:221], v[66:67], v[18:19] op_sel:[1,0,0]
	v_pk_fma_f32 v[16:17], v[220:221], v[64:65], v[16:17] op_sel:[1,0,0]
	v_pk_fma_f32 v[30:31], v[222:223], v[66:67], v[30:31] op_sel_hi:[0,1,1]
	v_pk_fma_f32 v[28:29], v[222:223], v[64:65], v[28:29] op_sel_hi:[0,1,1]
	v_pk_fma_f32 v[34:35], v[166:167], v[66:67], v[34:35] op_sel_hi:[0,1,1]
	v_pk_fma_f32 v[32:33], v[166:167], v[64:65], v[32:33] op_sel_hi:[0,1,1]
	v_pk_fma_f32 v[46:47], v[68:69], v[66:67], v[46:47] op_sel_hi:[0,1,1]
	v_pk_fma_f32 v[44:45], v[68:69], v[64:65], v[44:45] op_sel_hi:[0,1,1]
	v_mov_b32_e32 v64, v163
	v_pk_fma_f32 v[6:7], v[224:225], v[58:59], v[6:7] op_sel_hi:[0,1,1]
	v_pk_fma_f32 v[4:5], v[224:225], v[56:57], v[4:5] op_sel_hi:[0,1,1]
	v_pk_fma_f32 v[18:19], v[224:225], v[58:59], v[18:19] op_sel:[1,0,0]
	v_pk_fma_f32 v[16:17], v[224:225], v[56:57], v[16:17] op_sel:[1,0,0]
	v_pk_fma_f32 v[30:31], v[226:227], v[58:59], v[30:31] op_sel_hi:[0,1,1]
	v_pk_fma_f32 v[28:29], v[226:227], v[56:57], v[28:29] op_sel_hi:[0,1,1]
	v_pk_fma_f32 v[34:35], v[162:163], v[58:59], v[34:35] op_sel_hi:[0,1,1]
	v_pk_fma_f32 v[32:33], v[162:163], v[56:57], v[32:33] op_sel_hi:[0,1,1]
	v_pk_fma_f32 v[46:47], v[64:65], v[58:59], v[46:47] op_sel_hi:[0,1,1]
	v_pk_fma_f32 v[44:45], v[64:65], v[56:57], v[44:45] op_sel_hi:[0,1,1]
	v_mov_b32_e32 v56, v159
	v_pk_fma_f32 v[6:7], v[228:229], v[42:43], v[6:7] op_sel_hi:[0,1,1]
	v_pk_fma_f32 v[4:5], v[228:229], v[40:41], v[4:5] op_sel_hi:[0,1,1]
	v_pk_fma_f32 v[18:19], v[228:229], v[42:43], v[18:19] op_sel:[1,0,0]
	v_pk_fma_f32 v[16:17], v[228:229], v[40:41], v[16:17] op_sel:[1,0,0]
	v_pk_fma_f32 v[30:31], v[230:231], v[42:43], v[30:31] op_sel_hi:[0,1,1]
	v_pk_fma_f32 v[28:29], v[230:231], v[40:41], v[28:29] op_sel_hi:[0,1,1]
	v_pk_fma_f32 v[34:35], v[158:159], v[42:43], v[34:35] op_sel_hi:[0,1,1]
	v_pk_fma_f32 v[32:33], v[158:159], v[40:41], v[32:33] op_sel_hi:[0,1,1]
	v_pk_fma_f32 v[42:43], v[56:57], v[42:43], v[46:47] op_sel_hi:[0,1,1]
	v_pk_fma_f32 v[40:41], v[56:57], v[40:41], v[44:45] op_sel_hi:[0,1,1]
	v_mov_b32_e32 v44, v155
	v_pk_fma_f32 v[6:7], v[232:233], v[14:15], v[6:7] op_sel_hi:[0,1,1]
	v_pk_fma_f32 v[4:5], v[232:233], v[12:13], v[4:5] op_sel_hi:[0,1,1]
	v_pk_fma_f32 v[18:19], v[232:233], v[14:15], v[18:19] op_sel:[1,0,0]
	v_pk_fma_f32 v[16:17], v[232:233], v[12:13], v[16:17] op_sel:[1,0,0]
	v_pk_fma_f32 v[30:31], v[234:235], v[14:15], v[30:31] op_sel_hi:[0,1,1]
	v_pk_fma_f32 v[28:29], v[234:235], v[12:13], v[28:29] op_sel_hi:[0,1,1]
	v_pk_fma_f32 v[34:35], v[154:155], v[14:15], v[34:35] op_sel_hi:[0,1,1]
	v_pk_fma_f32 v[32:33], v[154:155], v[12:13], v[32:33] op_sel_hi:[0,1,1]
	v_pk_fma_f32 v[14:15], v[44:45], v[14:15], v[42:43] op_sel_hi:[0,1,1]
	v_pk_fma_f32 v[12:13], v[44:45], v[12:13], v[40:41] op_sel_hi:[0,1,1]
	v_mov_b32_e32 v40, v151
	v_pk_fma_f32 v[6:7], v[236:237], v[2:3], v[6:7] op_sel_hi:[0,1,1]
	v_pk_fma_f32 v[4:5], v[236:237], v[0:1], v[4:5] op_sel_hi:[0,1,1]
	v_pk_fma_f32 v[18:19], v[236:237], v[2:3], v[18:19] op_sel:[1,0,0]
	v_pk_fma_f32 v[16:17], v[236:237], v[0:1], v[16:17] op_sel:[1,0,0]
	v_pk_fma_f32 v[30:31], v[238:239], v[2:3], v[30:31] op_sel_hi:[0,1,1]
	v_pk_fma_f32 v[28:29], v[238:239], v[0:1], v[28:29] op_sel_hi:[0,1,1]
	v_pk_fma_f32 v[34:35], v[150:151], v[2:3], v[34:35] op_sel_hi:[0,1,1]
	v_pk_fma_f32 v[32:33], v[150:151], v[0:1], v[32:33] op_sel_hi:[0,1,1]
	v_pk_fma_f32 v[46:47], v[40:41], v[2:3], v[14:15] op_sel_hi:[0,1,1]
	v_pk_fma_f32 v[44:45], v[40:41], v[0:1], v[12:13] op_sel_hi:[0,1,1]
.LBB0_570:
	s_add_u32 s6, s10, s40
	v_sub_f32_e32 v0, v172, v192
	s_addc_u32 s7, s11, s41
	v_exp_f32_e32 v152, v0
	v_sub_f32_e32 v0, v178, v193
	s_add_u32 s40, s6, s44
	v_exp_f32_e32 v153, v0
	v_sub_f32_e32 v0, v180, v194
	s_addc_u32 s41, s7, 0
	v_exp_f32_e32 v154, v0
	v_lshl_add_u64 v[0:1], s[40:41], 0, v[168:169]
	v_add_co_u32_e64 v2, s[6:7], s14, v0
	v_mov_b32_e32 v183, v182
	s_nop 0
	v_addc_co_u32_e64 v3, s[6:7], 0, v1, s[6:7]
	global_load_dwordx4 v[100:103], v[2:3], off offset:-4096 nt
	global_load_dwordx4 v[68:71], v[2:3], off nt
	v_add_co_u32_e64 v2, s[6:7], s15, v0
	v_sub_f32_e32 v155, v170, v195
	s_nop 0
	v_addc_co_u32_e64 v3, s[6:7], 0, v1, s[6:7]
	global_load_dwordx4 v[64:67], v[2:3], off offset:-4096 nt
	global_load_dwordx4 v[56:59], v[2:3], off nt
	v_add_co_u32_e64 v2, s[6:7], s26, v0
	v_exp_f32_e32 v155, v155
	s_nop 0
	v_addc_co_u32_e64 v3, s[6:7], 0, v1, s[6:7]
	v_add_co_u32_e64 v0, s[6:7], s27, v0
	global_load_dwordx4 v[40:43], v[2:3], off offset:-4096 nt
	global_load_dwordx4 v[12:15], v[2:3], off nt
	v_addc_co_u32_e64 v1, s[6:7], 0, v1, s[6:7]
	s_min_u32 s6, s53, 29
	global_load_dwordx4 v[108:111], v168, s[40:41] nt
	s_nop 0
	global_load_dwordx4 v[0:3], v[0:1], off nt
	s_add_i32 s40, s6, 2
	s_lshr_b32 s6, s40, 3
	s_cmp_eq_u32 s6, 2
	s_cselect_b32 s7, s47, s49
	s_cmp_eq_u32 s6, 1
	s_cselect_b32 s6, s45, s7
	s_cmp_lt_u32 s53, 6
	s_cselect_b32 s6, s22, s6
	s_ashr_i32 s7, s6, 31
	s_lshl_b32 s40, s40, 15
	s_and_b32 s56, s40, 0x38000
	s_lshl_b64 s[40:41], s[6:7], 18
	s_add_u32 s6, s8, s40
	s_addc_u32 s7, s9, s41
	s_add_u32 s54, s6, s56
	s_waitcnt lgkmcnt(0)
	s_waitcnt vmcnt(24)
	ds_read_b128 v[196:199], v249
	ds_read_b128 v[200:203], v249 offset:1024
	ds_read_b128 v[204:207], v249 offset:2048
	ds_read_b128 v[208:211], v249 offset:3072
	ds_read_b128 v[212:215], v250
	ds_read_b128 v[216:219], v250 offset:1024
	ds_read_b128 v[220:223], v250 offset:2048
	ds_read_b128 v[224:227], v250 offset:3072
	s_waitcnt lgkmcnt(0)
	v_cvt_pk_bf16_f32 v196, v196, v197
	v_cvt_pk_bf16_f32 v197, v198, v199
	ds_write_b64 v181, v[196:197] offset:43008
	v_cvt_pk_bf16_f32 v200, v200, v201
	v_cvt_pk_bf16_f32 v201, v202, v203
	ds_write_b64 v181, v[200:201] offset:43552
	v_cvt_pk_bf16_f32 v204, v204, v205
	v_cvt_pk_bf16_f32 v205, v206, v207
	ds_write_b64 v181, v[204:205] offset:44096
	v_cvt_pk_bf16_f32 v208, v208, v209
	v_cvt_pk_bf16_f32 v209, v210, v211
	ds_write_b64 v181, v[208:209] offset:44640
	v_cvt_pk_bf16_f32 v212, v212, v213
	v_cvt_pk_bf16_f32 v213, v214, v215
	ds_write_b64 v181, v[212:213] offset:45184
	v_cvt_pk_bf16_f32 v216, v216, v217
	v_cvt_pk_bf16_f32 v217, v218, v219
	ds_write_b64 v181, v[216:217] offset:45728
	v_cvt_pk_bf16_f32 v220, v220, v221
	v_cvt_pk_bf16_f32 v221, v222, v223
	ds_write_b64 v181, v[220:221] offset:46272
	v_cvt_pk_bf16_f32 v224, v224, v225
	v_cvt_pk_bf16_f32 v225, v226, v227
	s_addc_u32 s55, s7, 0
	ds_write_b64 v181, v[224:225] offset:46816
	v_readlane_b32 s46, v152, 0
	v_readlane_b32 s44, v152, 16
	v_readlane_b32 s52, v154, 16
	s_add_i32 s84, s53, 3
	s_min_u32 s84, s84, 31
	s_lshr_b32 s85, s84, 3
	s_cmp_eq_u32 s85, 2
	s_cselect_b32 s86, s47, s49
	s_cmp_eq_u32 s85, 1
	s_cselect_b32 s86, s45, s86
	s_cmp_eq_u32 s85, 0
	s_cselect_b32 s86, s22, s86
	s_ashr_i32 s87, s86, 31
	s_lshl_b64 s[86:87], s[86:87], 18
	s_and_b32 s85, s84, 7
	s_lshl_b32 s85, s85, 15
	s_add_u32 s86, s86, s85
	s_addc_u32 s87, s87, 0
	s_add_u32 s80, s8, s86
	s_addc_u32 s81, s9, s87
	s_mov_b32 m0, s88
	s_nop 0
	global_load_lds_dwordx4 v168, s[80:81] nt
	s_add_u32 s80, s80, 0x1000
	s_addc_u32 s81, s81, 0
	s_add_u32 m0, m0, 0x400
	s_nop 0
	global_load_lds_dwordx4 v168, s[80:81] nt
	s_add_u32 s80, s80, 0x1000
	s_addc_u32 s81, s81, 0
	s_add_u32 m0, m0, 0x400
	s_nop 0
	global_load_lds_dwordx4 v168, s[80:81] nt
	s_add_u32 s80, s80, 0x1000
	s_addc_u32 s81, s81, 0
	s_add_u32 m0, m0, 0x400
	s_nop 0
	global_load_lds_dwordx4 v168, s[80:81] nt
	s_add_u32 s80, s80, 0x1000
	s_addc_u32 s81, s81, 0
	s_mov_b32 m0, s89
	s_nop 0
	global_load_lds_dwordx4 v168, s[80:81] nt
	s_add_u32 s80, s80, 0x1000
	s_addc_u32 s81, s81, 0
	s_add_u32 m0, m0, 0x400
	s_nop 0
	global_load_lds_dwordx4 v168, s[80:81] nt
	s_add_u32 s80, s80, 0x1000
	s_addc_u32 s81, s81, 0
	s_add_u32 m0, m0, 0x400
	s_nop 0
	global_load_lds_dwordx4 v168, s[80:81] nt
	s_add_u32 s80, s80, 0x1000
	s_addc_u32 s81, s81, 0
	s_add_u32 m0, m0, 0x400
	s_nop 0
	global_load_lds_dwordx4 v168, s[80:81] nt
	s_or_b32 s6, s42, s16
	v_add_u32_e32 v148, s6, v179
	v_add_u32_e32 v149, -1, v148
	v_add_u32_e32 v150, -2, v148
	v_add_u32_e32 v151, -3, v148
	s_waitcnt lgkmcnt(0)
	v_cvt_f32_i32_e32 v160, v148
	v_cvt_f32_i32_e32 v161, v149
	v_cvt_f32_i32_e32 v163, v151
	v_cvt_f32_i32_e32 v162, v150
	ds_read_b128 v[148:151], v190 offset:43008
	ds_read_b128 v[156:159], v190 offset:43072
	v_pk_mul_f32 v[160:161], v[184:185], v[160:161]
	v_readlane_b32 s42, v153, 0
	v_pk_mul_f32 v[162:163], v[182:183], v[162:163]
	v_readlane_b32 s16, v153, 16
	v_readlane_b32 s6, v154, 0
	s_waitcnt lgkmcnt(1)
	v_mfma_f32_16x16x32_bf16 v[148:151], v[24:27], v[148:151], v[160:163]
	v_readlane_b32 s50, v155, 0
	v_readlane_b32 s48, v155, 16
	s_nop 0
	ds_read_b128 v[160:163], v190 offset:43136
	s_waitcnt lgkmcnt(1)
	v_mfma_f32_16x16x32_bf16 v[148:151], v[48:51], v[156:159], v[148:151]
	ds_read_b128 v[156:159], v190 offset:43200
	s_waitcnt lgkmcnt(1)
	v_mfma_f32_16x16x32_bf16 v[148:151], v[52:55], v[160:163], v[148:151]
	s_waitcnt lgkmcnt(0)
	v_mfma_f32_16x16x32_bf16 v[148:151], v[60:63], v[156:159], v[148:151]
	s_nop 7
	v_mov_b32_dpp v156, v148 quad_perm:[1,0,3,2] row_mask:0xf bank_mask:0xf bound_ctrl:1
	v_max_f32_e32 v157, v148, v148
	v_max_f32_e32 v156, v156, v156
	v_max_f32_e32 v156, v157, v156
	s_nop 1
	v_mov_b32_dpp v157, v156 quad_perm:[2,3,0,1] row_mask:0xf bank_mask:0xf bound_ctrl:1
	v_max_f32_e32 v157, v157, v157
	v_max_f32_e32 v156, v156, v157
	s_nop 1
	v_mov_b32_dpp v157, v156 row_half_mirror row_mask:0xf bank_mask:0xf bound_ctrl:1
	v_max_f32_e32 v157, v157, v157
	v_max_f32_e32 v156, v156, v157
	s_nop 1
	v_mov_b32_dpp v157, v156 row_ror:8 row_mask:0xf bank_mask:0xf bound_ctrl:1
	v_max3_f32 v172, v192, v156, v157
	v_mov_b32_dpp v156, v149 quad_perm:[1,0,3,2] row_mask:0xf bank_mask:0xf bound_ctrl:1
	v_max_f32_e32 v157, v149, v149
	v_max_f32_e32 v156, v156, v156
	v_max_f32_e32 v156, v157, v156
	v_sub_f32_e32 v148, v148, v172
	v_exp_f32_e32 v148, v148
	v_mov_b32_dpp v157, v156 quad_perm:[2,3,0,1] row_mask:0xf bank_mask:0xf bound_ctrl:1
	v_max_f32_e32 v157, v157, v157
	v_max_f32_e32 v156, v156, v157
	s_nop 1
	v_mov_b32_dpp v157, v156 row_half_mirror row_mask:0xf bank_mask:0xf bound_ctrl:1
	v_max_f32_e32 v157, v157, v157
	v_max_f32_e32 v156, v156, v157
	s_nop 1
	v_mov_b32_dpp v157, v156 row_ror:8 row_mask:0xf bank_mask:0xf bound_ctrl:1
	v_max3_f32 v178, v193, v156, v157
	v_mov_b32_dpp v156, v150 quad_perm:[1,0,3,2] row_mask:0xf bank_mask:0xf bound_ctrl:1
	v_max_f32_e32 v157, v150, v150
	v_max_f32_e32 v156, v156, v156
	v_max_f32_e32 v156, v157, v156
	v_sub_f32_e32 v149, v149, v178
	v_exp_f32_e32 v149, v149
	v_mov_b32_dpp v157, v156 quad_perm:[2,3,0,1] row_mask:0xf bank_mask:0xf bound_ctrl:1
	v_max_f32_e32 v157, v157, v157
	v_max_f32_e32 v156, v156, v157
	s_nop 1
	v_mov_b32_dpp v157, v156 row_half_mirror row_mask:0xf bank_mask:0xf bound_ctrl:1
	v_max_f32_e32 v157, v157, v157
	v_max_f32_e32 v156, v156, v157
	s_nop 1
	v_mov_b32_dpp v157, v156 row_ror:8 row_mask:0xf bank_mask:0xf bound_ctrl:1
	v_max3_f32 v180, v194, v156, v157
	v_mov_b32_dpp v156, v151 quad_perm:[1,0,3,2] row_mask:0xf bank_mask:0xf bound_ctrl:1
	v_max_f32_e32 v157, v151, v151
	v_max_f32_e32 v156, v156, v156
	v_max_f32_e32 v156, v157, v156
	v_sub_f32_e32 v150, v150, v180
	v_exp_f32_e32 v150, v150
	v_mov_b32_dpp v157, v156 quad_perm:[2,3,0,1] row_mask:0xf bank_mask:0xf bound_ctrl:1
	v_max_f32_e32 v157, v157, v157
	v_max_f32_e32 v156, v156, v157
	s_nop 1
	v_mov_b32_dpp v157, v156 row_half_mirror row_mask:0xf bank_mask:0xf bound_ctrl:1
	v_max_f32_e32 v157, v157, v157
	v_max_f32_e32 v156, v156, v157
	s_nop 1
	v_mov_b32_dpp v157, v156 row_ror:8 row_mask:0xf bank_mask:0xf bound_ctrl:1
	v_max3_f32 v170, v195, v156, v157
	v_sub_f32_e32 v151, v151, v170
	v_exp_f32_e32 v151, v151
	s_and_saveexec_b64 s[54:55], vcc
	ds_write_b128 v191, v[148:151] offset:35328
	s_or_b64 exec, exec, s[54:55]
	v_pk_mul_f32 v[216:217], v[6:7], s[46:47] op_sel_hi:[1,0]
	v_pk_mul_f32 v[218:219], v[4:5], s[46:47] op_sel_hi:[1,0]
	v_pk_mul_f32 v[220:221], v[10:11], s[44:45] op_sel_hi:[1,0]
	v_pk_mul_f32 v[222:223], v[8:9], s[44:45] op_sel_hi:[1,0]
	v_pk_mul_f32 v[224:225], v[18:19], s[42:43] op_sel_hi:[1,0]
	v_pk_mul_f32 v[226:227], v[16:17], s[42:43] op_sel_hi:[1,0]
	v_pk_mul_f32 v[228:229], v[22:23], s[16:17] op_sel_hi:[1,0]
	v_pk_mul_f32 v[230:231], v[20:21], s[16:17] op_sel_hi:[1,0]
	v_pk_mul_f32 v[232:233], v[30:31], s[6:7] op_sel_hi:[1,0]
	v_pk_mul_f32 v[234:235], v[28:29], s[6:7] op_sel_hi:[1,0]
	v_pk_mul_f32 v[236:237], v[34:35], s[52:53] op_sel_hi:[1,0]
	v_pk_mul_f32 v[238:239], v[32:33], s[52:53] op_sel_hi:[1,0]
	v_pk_mul_f32 v[240:241], v[38:39], s[50:51] op_sel_hi:[1,0]
	v_pk_mul_f32 v[242:243], v[36:37], s[50:51] op_sel_hi:[1,0]
	v_pk_mul_f32 v[244:245], v[46:47], s[48:49] op_sel_hi:[1,0]
	v_pk_mul_f32 v[246:247], v[44:45], s[48:49] op_sel_hi:[1,0]
	s_waitcnt vmcnt(24)
	ds_read_b128 v[4:7], v173 offset:34816
	ds_read_b128 v[8:11], v173 offset:34832
	ds_read_b128 v[16:19], v173 offset:34880
	ds_read_b128 v[20:23], v173 offset:34896
	ds_read_b128 v[28:31], v173 offset:34944
	ds_read_b128 v[32:35], v173 offset:34960
	ds_read_b128 v[36:39], v173 offset:35008
	ds_read_b128 v[44:47], v173 offset:35024
	ds_read_b128 v[156:159], v173 offset:35072
	ds_read_b128 v[160:163], v173 offset:35088
	ds_read_b128 v[164:167], v173 offset:35136
	ds_read_b128 v[196:199], v173 offset:35152
	ds_read_b128 v[200:203], v173 offset:35200
	ds_read_b128 v[204:207], v173 offset:35216
	ds_read_b128 v[208:211], v173 offset:35264
	ds_read_b128 v[212:215], v173 offset:35280
	s_waitcnt lgkmcnt(14)
	v_pk_fma_f32 v[216:217], v[4:5], v[74:75], v[216:217] op_sel_hi:[0,1,1]
	v_pk_fma_f32 v[218:219], v[4:5], v[72:73], v[218:219] op_sel_hi:[0,1,1]
	v_pk_fma_f32 v[224:225], v[4:5], v[74:75], v[224:225] op_sel:[1,0,0]
	v_pk_fma_f32 v[4:5], v[4:5], v[72:73], v[226:227] op_sel:[1,0,0]
	s_waitcnt lgkmcnt(13)
	v_pk_fma_f32 v[218:219], v[16:17], v[80:81], v[218:219] op_sel_hi:[0,1,1]
	v_pk_fma_f32 v[4:5], v[16:17], v[80:81], v[4:5] op_sel:[1,0,0]
	v_pk_fma_f32 v[216:217], v[16:17], v[82:83], v[216:217] op_sel_hi:[0,1,1]
	s_waitcnt lgkmcnt(11)
	v_pk_fma_f32 v[4:5], v[28:29], v[76:77], v[4:5] op_sel:[1,0,0]
	v_pk_fma_f32 v[16:17], v[16:17], v[82:83], v[224:225] op_sel:[1,0,0]
	s_waitcnt lgkmcnt(9)
	v_pk_fma_f32 v[4:5], v[36:37], v[88:89], v[4:5] op_sel:[1,0,0]
	v_pk_fma_f32 v[216:217], v[28:29], v[78:79], v[216:217] op_sel_hi:[0,1,1]
	s_waitcnt lgkmcnt(7)
	v_pk_fma_f32 v[4:5], v[156:157], v[84:85], v[4:5] op_sel:[1,0,0]
	v_pk_fma_f32 v[218:219], v[28:29], v[76:77], v[218:219] op_sel_hi:[0,1,1]
	s_waitcnt lgkmcnt(5)
	v_pk_fma_f32 v[4:5], v[164:165], v[96:97], v[4:5] op_sel:[1,0,0]
	v_pk_fma_f32 v[16:17], v[28:29], v[78:79], v[16:17] op_sel:[1,0,0]
	s_waitcnt lgkmcnt(3)
	v_pk_fma_f32 v[4:5], v[200:201], v[92:93], v[4:5] op_sel:[1,0,0]
	v_pk_fma_f32 v[220:221], v[8:9], v[74:75], v[220:221] op_sel_hi:[0,1,1]
	s_waitcnt lgkmcnt(1)
	v_pk_fma_f32 v[28:29], v[208:209], v[104:105], v[4:5] op_sel:[1,0,0]
	v_pk_fma_f32 v[4:5], v[8:9], v[74:75], v[228:229] op_sel:[1,0,0]
	v_pk_fma_f32 v[222:223], v[8:9], v[72:73], v[222:223] op_sel_hi:[0,1,1]
	v_pk_fma_f32 v[8:9], v[8:9], v[72:73], v[230:231] op_sel:[1,0,0]
	v_pk_fma_f32 v[4:5], v[20:21], v[82:83], v[4:5] op_sel:[1,0,0]
	v_pk_fma_f32 v[8:9], v[20:21], v[80:81], v[8:9] op_sel:[1,0,0]
	v_pk_fma_f32 v[4:5], v[32:33], v[78:79], v[4:5] op_sel:[1,0,0]
	v_pk_fma_f32 v[8:9], v[32:33], v[76:77], v[8:9] op_sel:[1,0,0]
	v_pk_fma_f32 v[4:5], v[44:45], v[90:91], v[4:5] op_sel:[1,0,0]
	v_pk_fma_f32 v[8:9], v[44:45], v[88:89], v[8:9] op_sel:[1,0,0]
	v_pk_fma_f32 v[4:5], v[160:161], v[86:87], v[4:5] op_sel:[1,0,0]
	v_pk_fma_f32 v[8:9], v[160:161], v[84:85], v[8:9] op_sel:[1,0,0]
	v_pk_fma_f32 v[4:5], v[196:197], v[98:99], v[4:5] op_sel:[1,0,0]
	v_pk_fma_f32 v[222:223], v[20:21], v[80:81], v[222:223] op_sel_hi:[0,1,1]
	v_pk_fma_f32 v[220:221], v[20:21], v[82:83], v[220:221] op_sel_hi:[0,1,1]
	v_pk_fma_f32 v[8:9], v[196:197], v[96:97], v[8:9] op_sel:[1,0,0]
	v_pk_fma_f32 v[4:5], v[204:205], v[94:95], v[4:5] op_sel:[1,0,0]
	v_pk_fma_f32 v[220:221], v[32:33], v[78:79], v[220:221] op_sel_hi:[0,1,1]
	v_pk_fma_f32 v[222:223], v[32:33], v[76:77], v[222:223] op_sel_hi:[0,1,1]
	v_pk_fma_f32 v[8:9], v[204:205], v[92:93], v[8:9] op_sel:[1,0,0]
	s_waitcnt lgkmcnt(0)
	v_pk_fma_f32 v[32:33], v[212:213], v[106:107], v[4:5] op_sel:[1,0,0]
	v_pk_fma_f32 v[4:5], v[6:7], v[74:75], v[232:233] op_sel_hi:[0,1,1]
	v_pk_fma_f32 v[20:21], v[212:213], v[104:105], v[8:9] op_sel:[1,0,0]
	v_pk_fma_f32 v[8:9], v[6:7], v[72:73], v[234:235] op_sel_hi:[0,1,1]
	v_pk_fma_f32 v[4:5], v[18:19], v[82:83], v[4:5] op_sel_hi:[0,1,1]
	v_pk_fma_f32 v[8:9], v[18:19], v[80:81], v[8:9] op_sel_hi:[0,1,1]
	v_pk_fma_f32 v[4:5], v[30:31], v[78:79], v[4:5] op_sel_hi:[0,1,1]
	v_pk_fma_f32 v[8:9], v[30:31], v[76:77], v[8:9] op_sel_hi:[0,1,1]
	v_pk_fma_f32 v[4:5], v[38:39], v[90:91], v[4:5] op_sel_hi:[0,1,1]
	v_pk_fma_f32 v[8:9], v[38:39], v[88:89], v[8:9] op_sel_hi:[0,1,1]
	v_pk_fma_f32 v[4:5], v[158:159], v[86:87], v[4:5] op_sel_hi:[0,1,1]
	v_pk_fma_f32 v[8:9], v[158:159], v[84:85], v[8:9] op_sel_hi:[0,1,1]
	v_pk_fma_f32 v[4:5], v[166:167], v[98:99], v[4:5] op_sel_hi:[0,1,1]
	v_pk_fma_f32 v[8:9], v[166:167], v[96:97], v[8:9] op_sel_hi:[0,1,1]
	v_pk_fma_f32 v[4:5], v[202:203], v[94:95], v[4:5] op_sel_hi:[0,1,1]
	v_pk_fma_f32 v[222:223], v[44:45], v[88:89], v[222:223] op_sel_hi:[0,1,1]
	v_pk_fma_f32 v[220:221], v[44:45], v[90:91], v[220:221] op_sel_hi:[0,1,1]
	v_pk_fma_f32 v[8:9], v[202:203], v[92:93], v[8:9] op_sel_hi:[0,1,1]
	v_pk_fma_f32 v[44:45], v[210:211], v[106:107], v[4:5] op_sel_hi:[0,1,1]
	v_pk_fma_f32 v[4:5], v[10:11], v[74:75], v[236:237] op_sel_hi:[0,1,1]
	v_pk_fma_f32 v[218:219], v[36:37], v[88:89], v[218:219] op_sel_hi:[0,1,1]
	v_pk_fma_f32 v[216:217], v[36:37], v[90:91], v[216:217] op_sel_hi:[0,1,1]
	v_pk_fma_f32 v[16:17], v[36:37], v[90:91], v[16:17] op_sel:[1,0,0]
	v_pk_fma_f32 v[36:37], v[210:211], v[104:105], v[8:9] op_sel_hi:[0,1,1]
	v_pk_fma_f32 v[8:9], v[10:11], v[72:73], v[238:239] op_sel_hi:[0,1,1]
	v_pk_fma_f32 v[4:5], v[22:23], v[82:83], v[4:5] op_sel_hi:[0,1,1]
	v_pk_fma_f32 v[8:9], v[22:23], v[80:81], v[8:9] op_sel_hi:[0,1,1]
	v_pk_fma_f32 v[4:5], v[34:35], v[78:79], v[4:5] op_sel_hi:[0,1,1]
	v_pk_fma_f32 v[8:9], v[34:35], v[76:77], v[8:9] op_sel_hi:[0,1,1]
	v_pk_fma_f32 v[4:5], v[46:47], v[90:91], v[4:5] op_sel_hi:[0,1,1]
	v_pk_fma_f32 v[8:9], v[46:47], v[88:89], v[8:9] op_sel_hi:[0,1,1]
	v_pk_fma_f32 v[4:5], v[162:163], v[86:87], v[4:5] op_sel_hi:[0,1,1]
	v_pk_fma_f32 v[8:9], v[162:163], v[84:85], v[8:9] op_sel_hi:[0,1,1]
	v_pk_fma_f32 v[4:5], v[198:199], v[98:99], v[4:5] op_sel_hi:[0,1,1]
	v_pk_fma_f32 v[8:9], v[198:199], v[96:97], v[8:9] op_sel_hi:[0,1,1]
	v_pk_fma_f32 v[4:5], v[206:207], v[94:95], v[4:5] op_sel_hi:[0,1,1]
	v_pk_fma_f32 v[220:221], v[160:161], v[86:87], v[220:221] op_sel_hi:[0,1,1]
	v_pk_fma_f32 v[222:223], v[160:161], v[84:85], v[222:223] op_sel_hi:[0,1,1]
	v_pk_fma_f32 v[8:9], v[206:207], v[92:93], v[8:9] op_sel_hi:[0,1,1]
	v_pk_fma_f32 v[160:161], v[214:215], v[106:107], v[4:5] op_sel_hi:[0,1,1]
	v_mov_b32_e32 v4, v7
	v_pk_fma_f32 v[216:217], v[156:157], v[86:87], v[216:217] op_sel_hi:[0,1,1]
	v_pk_fma_f32 v[218:219], v[156:157], v[84:85], v[218:219] op_sel_hi:[0,1,1]
	v_pk_fma_f32 v[16:17], v[156:157], v[86:87], v[16:17] op_sel:[1,0,0]
	v_pk_fma_f32 v[156:157], v[214:215], v[104:105], v[8:9] op_sel_hi:[0,1,1]
	v_pk_fma_f32 v[6:7], v[4:5], v[74:75], v[240:241] op_sel_hi:[0,1,1]
	v_pk_fma_f32 v[4:5], v[4:5], v[72:73], v[242:243] op_sel_hi:[0,1,1]
	v_mov_b32_e32 v8, v19
	v_pk_fma_f32 v[4:5], v[8:9], v[80:81], v[4:5] op_sel_hi:[0,1,1]
	v_pk_fma_f32 v[6:7], v[8:9], v[82:83], v[6:7] op_sel_hi:[0,1,1]
	v_mov_b32_e32 v8, v31
	v_pk_fma_f32 v[6:7], v[8:9], v[78:79], v[6:7] op_sel_hi:[0,1,1]
	v_pk_fma_f32 v[4:5], v[8:9], v[76:77], v[4:5] op_sel_hi:[0,1,1]
	v_mov_b32_e32 v8, v39
	v_pk_fma_f32 v[4:5], v[8:9], v[88:89], v[4:5] op_sel_hi:[0,1,1]
	v_pk_fma_f32 v[6:7], v[8:9], v[90:91], v[6:7] op_sel_hi:[0,1,1]
	v_mov_b32_e32 v8, v159
	v_pk_fma_f32 v[6:7], v[8:9], v[86:87], v[6:7] op_sel_hi:[0,1,1]
	v_pk_fma_f32 v[4:5], v[8:9], v[84:85], v[4:5] op_sel_hi:[0,1,1]
	v_mov_b32_e32 v8, v167
	v_pk_fma_f32 v[4:5], v[8:9], v[96:97], v[4:5] op_sel_hi:[0,1,1]
	v_pk_fma_f32 v[6:7], v[8:9], v[98:99], v[6:7] op_sel_hi:[0,1,1]
	v_mov_b32_e32 v8, v203
	v_pk_fma_f32 v[6:7], v[8:9], v[94:95], v[6:7] op_sel_hi:[0,1,1]
	v_pk_fma_f32 v[4:5], v[8:9], v[92:93], v[4:5] op_sel_hi:[0,1,1]
	v_mov_b32_e32 v8, v211
	v_pk_fma_f32 v[158:159], v[8:9], v[104:105], v[4:5] op_sel_hi:[0,1,1]
	v_mov_b32_e32 v4, v11
	v_pk_fma_f32 v[38:39], v[8:9], v[106:107], v[6:7] op_sel_hi:[0,1,1]
	v_pk_fma_f32 v[6:7], v[4:5], v[74:75], v[244:245] op_sel_hi:[0,1,1]
	v_pk_fma_f32 v[4:5], v[4:5], v[72:73], v[246:247] op_sel_hi:[0,1,1]
	v_mov_b32_e32 v8, v23
	v_pk_fma_f32 v[4:5], v[8:9], v[80:81], v[4:5] op_sel_hi:[0,1,1]
	v_pk_fma_f32 v[6:7], v[8:9], v[82:83], v[6:7] op_sel_hi:[0,1,1]
	v_mov_b32_e32 v8, v35
	v_pk_fma_f32 v[6:7], v[8:9], v[78:79], v[6:7] op_sel_hi:[0,1,1]
	v_pk_fma_f32 v[4:5], v[8:9], v[76:77], v[4:5] op_sel_hi:[0,1,1]
	v_mov_b32_e32 v8, v47
	v_pk_fma_f32 v[4:5], v[8:9], v[88:89], v[4:5] op_sel_hi:[0,1,1]
	v_pk_fma_f32 v[6:7], v[8:9], v[90:91], v[6:7] op_sel_hi:[0,1,1]
	v_mov_b32_e32 v8, v163
	s_add_u32 s6, s10, s40
	v_pk_fma_f32 v[6:7], v[8:9], v[86:87], v[6:7] op_sel_hi:[0,1,1]
	v_pk_fma_f32 v[4:5], v[8:9], v[84:85], v[4:5] op_sel_hi:[0,1,1]
	v_mov_b32_e32 v8, v199
	s_addc_u32 s7, s11, s41
	v_pk_fma_f32 v[4:5], v[8:9], v[96:97], v[4:5] op_sel_hi:[0,1,1]
	v_pk_fma_f32 v[6:7], v[8:9], v[98:99], v[6:7] op_sel_hi:[0,1,1]
	v_mov_b32_e32 v8, v207
	s_add_u32 s40, s6, s56
	v_pk_fma_f32 v[6:7], v[8:9], v[94:95], v[6:7] op_sel_hi:[0,1,1]
	v_pk_fma_f32 v[4:5], v[8:9], v[92:93], v[4:5] op_sel_hi:[0,1,1]
	v_mov_b32_e32 v8, v215
	s_addc_u32 s41, s7, 0
	v_pk_fma_f32 v[162:163], v[8:9], v[104:105], v[4:5] op_sel_hi:[0,1,1]
	v_lshl_add_u64 v[4:5], s[40:41], 0, v[168:169]
	v_pk_fma_f32 v[46:47], v[8:9], v[106:107], v[6:7] op_sel_hi:[0,1,1]
	v_add_co_u32_e64 v6, s[6:7], s14, v4
	v_pk_fma_f32 v[218:219], v[164:165], v[96:97], v[218:219] op_sel_hi:[0,1,1]
	s_nop 0
	v_addc_co_u32_e64 v7, s[6:7], 0, v5, s[6:7]
	global_load_dwordx4 v[80:83], v[6:7], off offset:-4096 nt
	global_load_dwordx4 v[76:79], v[6:7], off nt
	v_add_co_u32_e64 v6, s[6:7], s15, v4
	v_pk_fma_f32 v[216:217], v[164:165], v[98:99], v[216:217] op_sel_hi:[0,1,1]
	s_nop 0
	v_addc_co_u32_e64 v7, s[6:7], 0, v5, s[6:7]
	global_load_dwordx4 v[88:91], v[6:7], off offset:-4096 nt
	global_load_dwordx4 v[84:87], v[6:7], off nt
	v_add_co_u32_e64 v6, s[6:7], s26, v4
	v_pk_fma_f32 v[222:223], v[196:197], v[96:97], v[222:223] op_sel_hi:[0,1,1]
	v_pk_fma_f32 v[220:221], v[196:197], v[98:99], v[220:221] op_sel_hi:[0,1,1]
	v_pk_fma_f32 v[16:17], v[164:165], v[98:99], v[16:17] op_sel:[1,0,0]
	v_addc_co_u32_e64 v7, s[6:7], 0, v5, s[6:7]
	v_pk_fma_f32 v[216:217], v[200:201], v[94:95], v[216:217] op_sel_hi:[0,1,1]
	v_pk_fma_f32 v[218:219], v[200:201], v[92:93], v[218:219] op_sel_hi:[0,1,1]
	v_pk_fma_f32 v[220:221], v[204:205], v[94:95], v[220:221] op_sel_hi:[0,1,1]
	v_pk_fma_f32 v[222:223], v[204:205], v[92:93], v[222:223] op_sel_hi:[0,1,1]
	v_pk_fma_f32 v[16:17], v[200:201], v[94:95], v[16:17] op_sel:[1,0,0]
	v_add_co_u32_e64 v4, s[6:7], s27, v4
	v_pk_fma_f32 v[218:219], v[208:209], v[104:105], v[218:219] op_sel_hi:[0,1,1]
	v_pk_fma_f32 v[216:217], v[208:209], v[106:107], v[216:217] op_sel_hi:[0,1,1]
	v_pk_fma_f32 v[222:223], v[212:213], v[104:105], v[222:223] op_sel_hi:[0,1,1]
	v_pk_fma_f32 v[220:221], v[212:213], v[106:107], v[220:221] op_sel_hi:[0,1,1]
	v_pk_fma_f32 v[16:17], v[208:209], v[106:107], v[16:17] op_sel:[1,0,0]
	global_load_dwordx4 v[96:99], v[6:7], off offset:-4096 nt
	global_load_dwordx4 v[92:95], v[6:7], off nt
	v_addc_co_u32_e64 v5, s[6:7], 0, v5, s[6:7]
	global_load_dwordx4 v[72:75], v168, s[40:41] nt
	global_load_dwordx4 v[104:107], v[4:5], off nt
	v_sub_f32_e32 v4, v192, v172
	v_exp_f32_e32 v18, v4
	v_sub_f32_e32 v4, v193, v178
	v_exp_f32_e32 v19, v4
	v_sub_f32_e32 v4, v194, v180
	v_exp_f32_e32 v164, v4
	v_sub_f32_e32 v4, v195, v170
	v_exp_f32_e32 v165, v4
	v_pk_fma_f32 v[4:5], v[174:175], v[152:153], v[112:113]
	v_pk_fma_f32 v[6:7], v[176:177], v[154:155], v[114:115]
	v_readlane_b32 s6, v18, 0
	v_pk_fma_f32 v[174:175], v[4:5], v[18:19], v[148:149]
	v_pk_fma_f32 v[176:177], v[6:7], v[164:165], v[150:151]
	v_readlane_b32 s16, v18, 16
	v_pk_mul_f32 v[6:7], v[216:217], s[6:7] op_sel_hi:[1,0]
	v_pk_mul_f32 v[4:5], v[218:219], s[6:7] op_sel_hi:[1,0]
	v_readlane_b32 s6, v19, 0
	v_pk_mul_f32 v[10:11], v[220:221], s[16:17] op_sel_hi:[1,0]
	v_pk_mul_f32 v[8:9], v[222:223], s[16:17] op_sel_hi:[1,0]
	v_readlane_b32 s16, v19, 16
	v_pk_mul_f32 v[18:19], v[16:17], s[6:7] op_sel_hi:[1,0]
	v_pk_mul_f32 v[16:17], v[28:29], s[6:7] op_sel_hi:[1,0]
	v_readlane_b32 s6, v164, 0
	v_pk_mul_f32 v[22:23], v[32:33], s[16:17] op_sel_hi:[1,0]
	v_pk_mul_f32 v[20:21], v[20:21], s[16:17] op_sel_hi:[1,0]
	v_readlane_b32 s16, v164, 16
	v_pk_mul_f32 v[30:31], v[44:45], s[6:7] op_sel_hi:[1,0]
	v_pk_mul_f32 v[28:29], v[36:37], s[6:7] op_sel_hi:[1,0]
	v_readlane_b32 s6, v165, 0
	s_waitcnt lgkmcnt(0)
	v_pk_mul_f32 v[34:35], v[160:161], s[16:17] op_sel_hi:[1,0]
	v_pk_mul_f32 v[32:33], v[156:157], s[16:17] op_sel_hi:[1,0]
	v_readlane_b32 s16, v165, 16
	v_pk_mul_f32 v[38:39], v[38:39], s[6:7] op_sel_hi:[1,0]
	v_pk_mul_f32 v[36:37], v[158:159], s[6:7] op_sel_hi:[1,0]
	s_add_i32 s6, s53, 2
	s_add_i32 s51, s51, 32
	v_pk_mul_f32 v[46:47], v[46:47], s[16:17] op_sel_hi:[1,0]
	v_pk_mul_f32 v[44:45], v[162:163], s[16:17] op_sel_hi:[1,0]
	s_cmp_gt_u32 s53, 29
	s_cbranch_scc1 .LBB0_574
	s_mov_b32 s53, s6
	s_branch .LBB0_566

	.amdhsa_kernel _Z6mk_fwdILi0ELi12EEv4Args
		.amdhsa_group_segment_fixed_size 0
		.amdhsa_private_segment_fixed_size 0
		.amdhsa_kernarg_size 504
		.amdhsa_user_sgpr_count 2
		.amdhsa_user_sgpr_dispatch_ptr 0
		.amdhsa_user_sgpr_queue_ptr 0
		.amdhsa_user_sgpr_kernarg_segment_ptr 1
		.amdhsa_user_sgpr_dispatch_id 0
		.amdhsa_user_sgpr_kernarg_preload_length 0
		.amdhsa_user_sgpr_kernarg_preload_offset 0
		.amdhsa_user_sgpr_private_segment_size 0
		.amdhsa_uses_dynamic_stack 0
		.amdhsa_enable_private_segment 0
		.amdhsa_system_sgpr_workgroup_id_x 1
		.amdhsa_system_sgpr_workgroup_id_y 0
		.amdhsa_system_sgpr_workgroup_id_z 0
		.amdhsa_system_sgpr_workgroup_info 0
		.amdhsa_system_vgpr_workitem_id 0
		.amdhsa_next_free_vgpr 251
		.amdhsa_next_free_sgpr 98
		.amdhsa_accum_offset 252
		.amdhsa_reserve_vcc 1
		.amdhsa_float_round_mode_32 0
		.amdhsa_float_round_mode_16_64 0
		.amdhsa_float_denorm_mode_32 3
		.amdhsa_float_denorm_mode_16_64 3
		.amdhsa_dx10_clamp 1
		.amdhsa_ieee_mode 1
		.amdhsa_fp16_overflow 0
		.amdhsa_tg_split 0
		.amdhsa_exception_fp_ieee_invalid_op 0
		.amdhsa_exception_fp_denorm_src 0
		.amdhsa_exception_fp_ieee_div_zero 0
		.amdhsa_exception_fp_ieee_overflow 0
		.amdhsa_exception_fp_ieee_underflow 0
		.amdhsa_exception_fp_ieee_inexact 0
		.amdhsa_exception_int_div_zero 0
	.end_amdhsa_kernel

amdhsa.kernels:
  - .agpr_count:     0
    .args:
      - .offset:         0
        .size:           248
        .value_kind:     by_value
      - .offset:         248
        .size:           4
        .value_kind:     hidden_block_count_x
      - .offset:         252
        .size:           4
        .value_kind:     hidden_block_count_y
      - .offset:         256
        .size:           4
        .value_kind:     hidden_block_count_z
      - .offset:         260
        .size:           2
        .value_kind:     hidden_group_size_x
      - .offset:         262
        .size:           2
        .value_kind:     hidden_group_size_y
      - .offset:         264
        .size:           2
        .value_kind:     hidden_group_size_z
      - .offset:         266
        .size:           2
        .value_kind:     hidden_remainder_x
      - .offset:         268
        .size:           2
        .value_kind:     hidden_remainder_y
      - .offset:         270
        .size:           2
        .value_kind:     hidden_remainder_z
      - .offset:         288
        .size:           8
        .value_kind:     hidden_global_offset_x
      - .offset:         296
        .size:           8
        .value_kind:     hidden_global_offset_y
      - .offset:         304
        .size:           8
        .value_kind:     hidden_global_offset_z
      - .offset:         312
        .size:           2
        .value_kind:     hidden_grid_dims
      - .offset:         368
        .size:           4
        .value_kind:     hidden_dynamic_lds_size
    .group_segment_fixed_size: 0
    .kernarg_segment_align: 8
    .kernarg_segment_size: 504
    .language:       OpenCL C
    .language_version:
      - 2
      - 0
    .max_flat_workgroup_size: 512
    .name:           _Z6mk_fwdILi0ELi12EEv4Args
    .private_segment_fixed_size: 0
    .sgpr_count:     104
    .sgpr_spill_count: 16
    .symbol:         _Z6mk_fwdILi0ELi12EEv4Args.kd
    .uniform_work_group_size: 1
    .uses_dynamic_stack: false
    .vgpr_count:     251
    .vgpr_spill_count: 0
    .wavefront_size: 64
